# LRU gates: clamp modifier on the 1-a^2 fma replaces the separate v_max (128 fewer VALU per tile)
# speedup vs baseline: 1.0027x; 1.0027x over previous
; __device__ __forceinline__ float bf2f(u16 h) { return __uint_as_float(((unsigned)h) << 16); }
; __device__ __forceinline__ void lru_tile(const Params& P, int chunk, int head, int pass, char* smem_raw) {
;     ...
;       f32x4 acc[8];
; #pragma unroll
;       for (int t = 0; t < 8; ++t) acc[t] = f32x4{0.f, 0.f, 0.f, 0.f};
; #pragma unroll
;       for (int s = 0; s < 2; ++s) {
;         const bf16x8 af = *reinterpret_cast<const bf16x8*>(&sm_uc[(sb * 64 + wid * 16 + (lane & 15)) * LDSS + s * 32 + (lane >> 4) * 8]);
; #pragma unroll
;         for (int t = 0; t < 8; ++t) {
;           const bf16x8 bfr = *reinterpret_cast<const bf16x8*>(&sm_w[(t * 16 + (lane & 15)) * LDSS + s * 32 + (lane >> 4) * 8]);
;           acc[t] = __builtin_amdgcn_mfma_f32_16x16x32_bf16(af, bfr, acc[t], 0, 0, 0);
;         }
;       }
; #pragma unroll
;       for (int tc = 0; tc < 4; ++tc)
; #pragma unroll
;         for (int reg = 0; reg < 4; ++reg) {
;           const int tl = wid * 16 + (lane >> 4) * 4 + reg;
;           const int c = 16 * tc + (lane & 15);
;           const float r = __builtin_amdgcn_rcpf(1.f + __builtin_amdgcn_exp2f(acc[tc][reg] + ba[tc]));
;           const float ii = __builtin_amdgcn_rcpf(1.f + __builtin_amdgcn_exp2f(acc[tc + 4][reg] + bi[tc]));
;           const float la = -c8[tc] * r;
;           const float a = __builtin_amdgcn_exp2f(la);
;           const float ucv = bf2f(sm_uc[(sb * 64 + tl) * LDSS + c]);
;           const float bt = __builtin_amdgcn_sqrtf(fmaxf(1.f - a * a, 0.f)) * (ii * ucv);
;           sm_a[tl * 64 + c] = a;
;           sm_b[tl * 64 + c] = bt;
;         }
.Lmy_lrua_nopf:
	ds_read_b128 v[76:79], v131 offset:0
	ds_read_b128 v[80:83], v133 offset:0
	ds_read_b128 v[122:125], v131 offset:512
	ds_read_b128 v[126:129], v133 offset:512
	s_waitcnt lgkmcnt(3)
	v_mfma_f32_16x16x32_bf16 v[0:3], v[76:79], v[238:241], 0
	v_mfma_f32_16x16x32_bf16 v[90:93], v[76:79], v[246:249], 0
	ds_read_b128 v[76:79], v131 offset:1024
	s_waitcnt lgkmcnt(3)
	v_mfma_f32_16x16x32_bf16 v[0:3], v[80:83], v[242:245], v[0:3]
	v_mfma_f32_16x16x32_bf16 v[90:93], v[80:83], v[194:197], v[90:93]
	ds_read_b128 v[80:83], v133 offset:1024
	s_waitcnt lgkmcnt(3)
	v_mfma_f32_16x16x32_bf16 v[4:7], v[122:125], v[238:241], 0
	v_mfma_f32_16x16x32_bf16 v[94:97], v[122:125], v[246:249], 0
	ds_read_b128 v[122:125], v131 offset:1536
	s_waitcnt lgkmcnt(3)
	v_mfma_f32_16x16x32_bf16 v[4:7], v[126:129], v[242:245], v[4:7]
	v_mfma_f32_16x16x32_bf16 v[94:97], v[126:129], v[194:197], v[94:97]
	ds_read_b128 v[126:129], v133 offset:1536
	s_waitcnt lgkmcnt(3)
	v_mfma_f32_16x16x32_bf16 v[8:11], v[76:79], v[238:241], 0
	v_mfma_f32_16x16x32_bf16 v[98:101], v[76:79], v[246:249], 0
	ds_read_b128 v[76:79], v131 offset:2048
	s_waitcnt lgkmcnt(3)
	v_mfma_f32_16x16x32_bf16 v[8:11], v[80:83], v[242:245], v[8:11]
	v_mfma_f32_16x16x32_bf16 v[98:101], v[80:83], v[194:197], v[98:101]
	ds_read_b128 v[80:83], v133 offset:2048
	s_waitcnt lgkmcnt(3)
	v_mfma_f32_16x16x32_bf16 v[12:15], v[122:125], v[238:241], 0
	v_mfma_f32_16x16x32_bf16 v[102:105], v[122:125], v[246:249], 0
	ds_read_b128 v[122:125], v131 offset:2560
	s_waitcnt lgkmcnt(3)
	v_mfma_f32_16x16x32_bf16 v[12:15], v[126:129], v[242:245], v[12:15]
	v_mfma_f32_16x16x32_bf16 v[102:105], v[126:129], v[194:197], v[102:105]
	ds_read_b128 v[126:129], v133 offset:2560
	s_waitcnt lgkmcnt(3)
	v_mfma_f32_16x16x32_bf16 v[16:19], v[76:79], v[238:241], 0
	v_mfma_f32_16x16x32_bf16 v[106:109], v[76:79], v[246:249], 0
	ds_read_b128 v[76:79], v131 offset:3072
	s_waitcnt lgkmcnt(3)
	v_mfma_f32_16x16x32_bf16 v[16:19], v[80:83], v[242:245], v[16:19]
	v_mfma_f32_16x16x32_bf16 v[106:109], v[80:83], v[194:197], v[106:109]
	ds_read_b128 v[80:83], v133 offset:3072
	s_waitcnt lgkmcnt(3)
	v_mfma_f32_16x16x32_bf16 v[20:23], v[122:125], v[238:241], 0
	v_mfma_f32_16x16x32_bf16 v[110:113], v[122:125], v[246:249], 0
	ds_read_b128 v[122:125], v131 offset:3584
	s_waitcnt lgkmcnt(3)
	v_mfma_f32_16x16x32_bf16 v[20:23], v[126:129], v[242:245], v[20:23]
	v_mfma_f32_16x16x32_bf16 v[110:113], v[126:129], v[194:197], v[110:113]
	ds_read_b128 v[126:129], v133 offset:3584
	s_waitcnt lgkmcnt(3)
	v_mfma_f32_16x16x32_bf16 v[24:27], v[76:79], v[238:241], 0
	v_mfma_f32_16x16x32_bf16 v[114:117], v[76:79], v[246:249], 0
	s_waitcnt lgkmcnt(2)
	v_mfma_f32_16x16x32_bf16 v[24:27], v[80:83], v[242:245], v[24:27]
	v_mfma_f32_16x16x32_bf16 v[114:117], v[80:83], v[194:197], v[114:117]
	s_waitcnt lgkmcnt(1)
	v_mfma_f32_16x16x32_bf16 v[28:31], v[122:125], v[238:241], 0
	v_mfma_f32_16x16x32_bf16 v[118:121], v[122:125], v[246:249], 0
	s_waitcnt lgkmcnt(0)
	v_mfma_f32_16x16x32_bf16 v[28:31], v[126:129], v[242:245], v[28:31]
	v_mfma_f32_16x16x32_bf16 v[118:121], v[126:129], v[194:197], v[118:121]
	s_lshl_b32 s0, s56, 8
	s_add_u32 s0, s0, 0x20000
	s_add_u32 s4, s20, s0
	s_addc_u32 s5, s21, 0
	global_load_dwordx4 v[238:241], v251, s[4:5]
	global_load_dwordx4 v[242:245], v251, s[4:5] offset:64
	s_add_u32 s4, s4, 0x2000
	s_addc_u32 s5, s5, 0
	global_load_dwordx4 v[246:249], v251, s[4:5]
	global_load_dwordx4 v[194:197], v251, s[4:5] offset:64
	s_nop 7
	s_nop 7
	v_add_f32_e32 v0, v0, v75
	v_add_f32_e32 v1, v1, v75
	v_add_f32_e32 v2, v2, v75
	v_add_f32_e32 v3, v3, v75
	v_add_f32_e32 v90, v90, v84
	v_add_f32_e32 v91, v91, v84
	v_add_f32_e32 v92, v92, v84
	v_add_f32_e32 v93, v93, v84
	v_exp_f32_e32 v0, v0
	v_exp_f32_e32 v1, v1
	v_exp_f32_e32 v2, v2
	v_exp_f32_e32 v3, v3
	v_exp_f32_e32 v90, v90
	v_exp_f32_e32 v91, v91
	v_exp_f32_e32 v92, v92
	v_exp_f32_e32 v93, v93
	v_add_f32_e32 v0, 1.0, v0
	v_add_f32_e32 v1, 1.0, v1
	v_add_f32_e32 v2, 1.0, v2
	v_add_f32_e32 v3, 1.0, v3
	v_add_f32_e32 v90, 1.0, v90
	v_add_f32_e32 v91, 1.0, v91
	v_add_f32_e32 v92, 1.0, v92
	v_add_f32_e32 v93, 1.0, v93
	v_rcp_f32_e32 v0, v0
	v_rcp_f32_e32 v1, v1
	v_rcp_f32_e32 v2, v2
	v_rcp_f32_e32 v3, v3
	v_rcp_f32_e32 v90, v90
	v_rcp_f32_e32 v91, v91
	v_rcp_f32_e32 v92, v92
	v_rcp_f32_e32 v93, v93
	v_mul_f32_e32 v0, v85, v0
	v_mul_f32_e32 v1, v85, v1
	v_mul_f32_e32 v2, v85, v2
	v_mul_f32_e32 v3, v85, v3
	v_mul_f32_e32 v90, v90, v162
	v_mul_f32_e32 v91, v91, v163
	v_mul_f32_e32 v92, v92, v164
	v_mul_f32_e32 v93, v93, v165
	v_exp_f32_e32 v0, v0
	v_exp_f32_e32 v1, v1
	v_exp_f32_e32 v2, v2
	v_exp_f32_e32 v3, v3
	s_nop 0
	v_fma_f32 v138, -v0, v0, 1.0 clamp
	v_fma_f32 v139, -v1, v1, 1.0 clamp
	v_fma_f32 v140, -v2, v2, 1.0 clamp
	v_fma_f32 v141, -v3, v3, 1.0 clamp
	v_sqrt_f32_e32 v138, v138
	v_sqrt_f32_e32 v139, v139
	v_sqrt_f32_e32 v140, v140
	v_sqrt_f32_e32 v141, v141
	s_nop 0
	v_mul_f32_e32 v90, v138, v90
	v_mul_f32_e32 v91, v139, v91
	v_mul_f32_e32 v92, v140, v92
	v_mul_f32_e32 v93, v141, v93
	v_add_f32_e32 v4, v4, v75
	v_add_f32_e32 v5, v5, v75
	v_add_f32_e32 v6, v6, v75
	v_add_f32_e32 v7, v7, v75
	v_add_f32_e32 v94, v94, v84
	v_add_f32_e32 v95, v95, v84
	v_add_f32_e32 v96, v96, v84
	v_add_f32_e32 v97, v97, v84
	v_exp_f32_e32 v4, v4
	v_exp_f32_e32 v5, v5
	v_exp_f32_e32 v6, v6
	v_exp_f32_e32 v7, v7
	v_exp_f32_e32 v94, v94
	v_exp_f32_e32 v95, v95
	v_exp_f32_e32 v96, v96
	v_exp_f32_e32 v97, v97
	v_add_f32_e32 v4, 1.0, v4
	v_add_f32_e32 v5, 1.0, v5
	v_add_f32_e32 v6, 1.0, v6
	v_add_f32_e32 v7, 1.0, v7
	v_add_f32_e32 v94, 1.0, v94
	v_add_f32_e32 v95, 1.0, v95
	v_add_f32_e32 v96, 1.0, v96
	v_add_f32_e32 v97, 1.0, v97
; __device__ __forceinline__ float bf2f(u16 h) { return __uint_as_float(((unsigned)h) << 16); }
; __device__ __forceinline__ void lru_tile(const Params& P, int chunk, int head, int pass, char* smem_raw) {
;     ...
;       for (int tc = 0; tc < 4; ++tc)
; #pragma unroll
;         for (int reg = 0; reg < 4; ++reg) {
;           const int tl = wid * 16 + (lane >> 4) * 4 + reg;
;           const int c = 16 * tc + (lane & 15);
;           const float r = __builtin_amdgcn_rcpf(1.f + __builtin_amdgcn_exp2f(acc[tc][reg] + ba[tc]));
;           const float ii = __builtin_amdgcn_rcpf(1.f + __builtin_amdgcn_exp2f(acc[tc + 4][reg] + bi[tc]));
;           const float la = -c8[tc] * r;
;           const float a = __builtin_amdgcn_exp2f(la);
;           const float ucv = bf2f(sm_uc[(sb * 64 + tl) * LDSS + c]);
;           const float bt = __builtin_amdgcn_sqrtf(fmaxf(1.f - a * a, 0.f)) * (ii * ucv);
;           sm_a[tl * 64 + c] = a;
;           sm_b[tl * 64 + c] = bt;
;         }
	v_rcp_f32_e32 v4, v4
	v_rcp_f32_e32 v5, v5
	v_rcp_f32_e32 v6, v6
	v_rcp_f32_e32 v7, v7
	v_rcp_f32_e32 v94, v94
	v_rcp_f32_e32 v95, v95
	v_rcp_f32_e32 v96, v96
	v_rcp_f32_e32 v97, v97
	v_mul_f32_e32 v4, v85, v4
	v_mul_f32_e32 v5, v85, v5
	v_mul_f32_e32 v6, v85, v6
	v_mul_f32_e32 v7, v85, v7
	v_mul_f32_e32 v94, v94, v166
	v_mul_f32_e32 v95, v95, v167
	v_mul_f32_e32 v96, v96, v168
	v_mul_f32_e32 v97, v97, v169
	v_exp_f32_e32 v4, v4
	v_exp_f32_e32 v5, v5
	v_exp_f32_e32 v6, v6
	v_exp_f32_e32 v7, v7
	s_nop 0
	v_fma_f32 v138, -v4, v4, 1.0 clamp
	v_fma_f32 v139, -v5, v5, 1.0 clamp
	v_fma_f32 v140, -v6, v6, 1.0 clamp
	v_fma_f32 v141, -v7, v7, 1.0 clamp
	v_sqrt_f32_e32 v138, v138
	v_sqrt_f32_e32 v139, v139
	v_sqrt_f32_e32 v140, v140
	v_sqrt_f32_e32 v141, v141
	s_nop 0
	v_mul_f32_e32 v94, v138, v94
	v_mul_f32_e32 v95, v139, v95
	v_mul_f32_e32 v96, v140, v96
	v_mul_f32_e32 v97, v141, v97
	v_add_f32_e32 v8, v8, v75
	v_add_f32_e32 v9, v9, v75
	v_add_f32_e32 v10, v10, v75
	v_add_f32_e32 v11, v11, v75
	v_add_f32_e32 v98, v98, v84
	v_add_f32_e32 v99, v99, v84
	v_add_f32_e32 v100, v100, v84
	v_add_f32_e32 v101, v101, v84
	v_exp_f32_e32 v8, v8
	v_exp_f32_e32 v9, v9
	v_exp_f32_e32 v10, v10
	v_exp_f32_e32 v11, v11
	v_exp_f32_e32 v98, v98
	v_exp_f32_e32 v99, v99
	v_exp_f32_e32 v100, v100
	v_exp_f32_e32 v101, v101
	v_add_f32_e32 v8, 1.0, v8
	v_add_f32_e32 v9, 1.0, v9
	v_add_f32_e32 v10, 1.0, v10
	v_add_f32_e32 v11, 1.0, v11
	v_add_f32_e32 v98, 1.0, v98
	v_add_f32_e32 v99, 1.0, v99
	v_add_f32_e32 v100, 1.0, v100
	v_add_f32_e32 v101, 1.0, v101
	v_rcp_f32_e32 v8, v8
	v_rcp_f32_e32 v9, v9
	v_rcp_f32_e32 v10, v10
	v_rcp_f32_e32 v11, v11
	v_rcp_f32_e32 v98, v98
	v_rcp_f32_e32 v99, v99
	v_rcp_f32_e32 v100, v100
	v_rcp_f32_e32 v101, v101
	v_mul_f32_e32 v8, v85, v8
	v_mul_f32_e32 v9, v85, v9
	v_mul_f32_e32 v10, v85, v10
	v_mul_f32_e32 v11, v85, v11
	v_mul_f32_e32 v98, v98, v170
	v_mul_f32_e32 v99, v99, v171
	v_mul_f32_e32 v100, v100, v172
	v_mul_f32_e32 v101, v101, v173
	v_exp_f32_e32 v8, v8
	v_exp_f32_e32 v9, v9
	v_exp_f32_e32 v10, v10
	v_exp_f32_e32 v11, v11
	s_nop 0
	v_fma_f32 v138, -v8, v8, 1.0 clamp
	v_fma_f32 v139, -v9, v9, 1.0 clamp
	v_fma_f32 v140, -v10, v10, 1.0 clamp
	v_fma_f32 v141, -v11, v11, 1.0 clamp
	v_sqrt_f32_e32 v138, v138
	v_sqrt_f32_e32 v139, v139
	v_sqrt_f32_e32 v140, v140
	v_sqrt_f32_e32 v141, v141
	s_nop 0
	v_mul_f32_e32 v98, v138, v98
	v_mul_f32_e32 v99, v139, v99
	v_mul_f32_e32 v100, v140, v100
	v_mul_f32_e32 v101, v141, v101
	v_add_f32_e32 v12, v12, v75
	v_add_f32_e32 v13, v13, v75
	v_add_f32_e32 v14, v14, v75
	v_add_f32_e32 v15, v15, v75
	v_add_f32_e32 v102, v102, v84
	v_add_f32_e32 v103, v103, v84
	v_add_f32_e32 v104, v104, v84
	v_add_f32_e32 v105, v105, v84
	v_exp_f32_e32 v12, v12
	v_exp_f32_e32 v13, v13
	v_exp_f32_e32 v14, v14
	v_exp_f32_e32 v15, v15
	v_exp_f32_e32 v102, v102
	v_exp_f32_e32 v103, v103
	v_exp_f32_e32 v104, v104
	v_exp_f32_e32 v105, v105
	v_add_f32_e32 v12, 1.0, v12
	v_add_f32_e32 v13, 1.0, v13
	v_add_f32_e32 v14, 1.0, v14
	v_add_f32_e32 v15, 1.0, v15
	v_add_f32_e32 v102, 1.0, v102
	v_add_f32_e32 v103, 1.0, v103
	v_add_f32_e32 v104, 1.0, v104
	v_add_f32_e32 v105, 1.0, v105
	v_rcp_f32_e32 v12, v12
	v_rcp_f32_e32 v13, v13
	v_rcp_f32_e32 v14, v14
	v_rcp_f32_e32 v15, v15
	v_rcp_f32_e32 v102, v102
	v_rcp_f32_e32 v103, v103
	v_rcp_f32_e32 v104, v104
	v_rcp_f32_e32 v105, v105
	v_mul_f32_e32 v12, v85, v12
	v_mul_f32_e32 v13, v85, v13
	v_mul_f32_e32 v14, v85, v14
	v_mul_f32_e32 v15, v85, v15
	v_mul_f32_e32 v102, v102, v174
	v_mul_f32_e32 v103, v103, v175
	v_mul_f32_e32 v104, v104, v176
	v_mul_f32_e32 v105, v105, v177
	v_exp_f32_e32 v12, v12
	v_exp_f32_e32 v13, v13
	v_exp_f32_e32 v14, v14
	v_exp_f32_e32 v15, v15
	s_nop 0
	v_fma_f32 v138, -v12, v12, 1.0 clamp
	v_fma_f32 v139, -v13, v13, 1.0 clamp
	v_fma_f32 v140, -v14, v14, 1.0 clamp
	v_fma_f32 v141, -v15, v15, 1.0 clamp
	v_sqrt_f32_e32 v138, v138
	v_sqrt_f32_e32 v139, v139
	v_sqrt_f32_e32 v140, v140
	v_sqrt_f32_e32 v141, v141
	s_nop 0
	v_mul_f32_e32 v102, v138, v102
	v_mul_f32_e32 v103, v139, v103
	v_mul_f32_e32 v104, v140, v104
	v_mul_f32_e32 v105, v141, v105
	v_add_f32_e32 v16, v16, v75
	v_add_f32_e32 v17, v17, v75
	v_add_f32_e32 v18, v18, v75
	v_add_f32_e32 v19, v19, v75
	v_add_f32_e32 v106, v106, v84
	v_add_f32_e32 v107, v107, v84
	v_add_f32_e32 v108, v108, v84
	v_add_f32_e32 v109, v109, v84
	v_exp_f32_e32 v16, v16
	v_exp_f32_e32 v17, v17
	v_exp_f32_e32 v18, v18
	v_exp_f32_e32 v19, v19
	v_exp_f32_e32 v106, v106
	v_exp_f32_e32 v107, v107
	v_exp_f32_e32 v108, v108
	v_exp_f32_e32 v109, v109
	v_add_f32_e32 v16, 1.0, v16
	v_add_f32_e32 v17, 1.0, v17
	v_add_f32_e32 v18, 1.0, v18
	v_add_f32_e32 v19, 1.0, v19
	v_add_f32_e32 v106, 1.0, v106
	v_add_f32_e32 v107, 1.0, v107
	v_add_f32_e32 v108, 1.0, v108
	v_add_f32_e32 v109, 1.0, v109
	v_rcp_f32_e32 v16, v16
	v_rcp_f32_e32 v17, v17
	v_rcp_f32_e32 v18, v18
	v_rcp_f32_e32 v19, v19
	v_rcp_f32_e32 v106, v106
	v_rcp_f32_e32 v107, v107
	v_rcp_f32_e32 v108, v108
	v_rcp_f32_e32 v109, v109
	v_mul_f32_e32 v16, v85, v16
	v_mul_f32_e32 v17, v85, v17
	v_mul_f32_e32 v18, v85, v18
	v_mul_f32_e32 v19, v85, v19
	v_mul_f32_e32 v106, v106, v178
	v_mul_f32_e32 v107, v107, v179
	v_mul_f32_e32 v108, v108, v180
	v_mul_f32_e32 v109, v109, v181
	v_exp_f32_e32 v16, v16
	v_exp_f32_e32 v17, v17
	v_exp_f32_e32 v18, v18
	v_exp_f32_e32 v19, v19
	s_nop 0
	v_fma_f32 v138, -v16, v16, 1.0 clamp
	v_fma_f32 v139, -v17, v17, 1.0 clamp
	v_fma_f32 v140, -v18, v18, 1.0 clamp
	v_fma_f32 v141, -v19, v19, 1.0 clamp
	v_sqrt_f32_e32 v138, v138
	v_sqrt_f32_e32 v139, v139
	v_sqrt_f32_e32 v140, v140
	v_sqrt_f32_e32 v141, v141
	s_nop 0
	v_mul_f32_e32 v106, v138, v106
	v_mul_f32_e32 v107, v139, v107
; __device__ __forceinline__ float bf2f(u16 h) { return __uint_as_float(((unsigned)h) << 16); }
; __device__ __forceinline__ void lru_tile(const Params& P, int chunk, int head, int pass, char* smem_raw) {
;     ...
;       for (int tc = 0; tc < 4; ++tc)
; #pragma unroll
;         for (int reg = 0; reg < 4; ++reg) {
;           const int tl = wid * 16 + (lane >> 4) * 4 + reg;
;           const int c = 16 * tc + (lane & 15);
;           const float r = __builtin_amdgcn_rcpf(1.f + __builtin_amdgcn_exp2f(acc[tc][reg] + ba[tc]));
;           const float ii = __builtin_amdgcn_rcpf(1.f + __builtin_amdgcn_exp2f(acc[tc + 4][reg] + bi[tc]));
;           const float la = -c8[tc] * r;
;           const float a = __builtin_amdgcn_exp2f(la);
;           const float ucv = bf2f(sm_uc[(sb * 64 + tl) * LDSS + c]);
;           const float bt = __builtin_amdgcn_sqrtf(fmaxf(1.f - a * a, 0.f)) * (ii * ucv);
;           sm_a[tl * 64 + c] = a;
;           sm_b[tl * 64 + c] = bt;
;         }
;       __syncthreads();
;       const int pos = (d == 0) ? q : 3 - q;
;       {
;         float Pp = 1.f, H = 0.f;
; #pragma unroll 4
;         for (int i = 0; i < 16; ++i) {
;           const int tl = (d == 0) ? (q * 16 + i) : (q * 16 + 15 - i);
;           const float a = sm_a[tl * 64 + ch], b = sm_b[tl * 64 + ch];
;           H = a * H + b; Pp *= a;
;         }
;         sm_ph[pos * 64 + ch] = make_float2(Pp, H);
	v_mul_f32_e32 v108, v140, v108
	v_mul_f32_e32 v109, v141, v109
	v_add_f32_e32 v20, v20, v75
	v_add_f32_e32 v21, v21, v75
	v_add_f32_e32 v22, v22, v75
	v_add_f32_e32 v23, v23, v75
	v_add_f32_e32 v110, v110, v84
	v_add_f32_e32 v111, v111, v84
	v_add_f32_e32 v112, v112, v84
	v_add_f32_e32 v113, v113, v84
	v_exp_f32_e32 v20, v20
	v_exp_f32_e32 v21, v21
	v_exp_f32_e32 v22, v22
	v_exp_f32_e32 v23, v23
	v_exp_f32_e32 v110, v110
	v_exp_f32_e32 v111, v111
	v_exp_f32_e32 v112, v112
	v_exp_f32_e32 v113, v113
	v_add_f32_e32 v20, 1.0, v20
	v_add_f32_e32 v21, 1.0, v21
	v_add_f32_e32 v22, 1.0, v22
	v_add_f32_e32 v23, 1.0, v23
	v_add_f32_e32 v110, 1.0, v110
	v_add_f32_e32 v111, 1.0, v111
	v_add_f32_e32 v112, 1.0, v112
	v_add_f32_e32 v113, 1.0, v113
	v_rcp_f32_e32 v20, v20
	v_rcp_f32_e32 v21, v21
	v_rcp_f32_e32 v22, v22
	v_rcp_f32_e32 v23, v23
	v_rcp_f32_e32 v110, v110
	v_rcp_f32_e32 v111, v111
	v_rcp_f32_e32 v112, v112
	v_rcp_f32_e32 v113, v113
	v_mul_f32_e32 v20, v85, v20
	v_mul_f32_e32 v21, v85, v21
	v_mul_f32_e32 v22, v85, v22
	v_mul_f32_e32 v23, v85, v23
	v_mul_f32_e32 v110, v110, v182
	v_mul_f32_e32 v111, v111, v183
	v_mul_f32_e32 v112, v112, v184
	v_mul_f32_e32 v113, v113, v185
	v_exp_f32_e32 v20, v20
	v_exp_f32_e32 v21, v21
	v_exp_f32_e32 v22, v22
	v_exp_f32_e32 v23, v23
	s_nop 0
	v_fma_f32 v138, -v20, v20, 1.0 clamp
	v_fma_f32 v139, -v21, v21, 1.0 clamp
	v_fma_f32 v140, -v22, v22, 1.0 clamp
	v_fma_f32 v141, -v23, v23, 1.0 clamp
	v_sqrt_f32_e32 v138, v138
	v_sqrt_f32_e32 v139, v139
	v_sqrt_f32_e32 v140, v140
	v_sqrt_f32_e32 v141, v141
	s_nop 0
	v_mul_f32_e32 v110, v138, v110
	v_mul_f32_e32 v111, v139, v111
	v_mul_f32_e32 v112, v140, v112
	v_mul_f32_e32 v113, v141, v113
	v_add_f32_e32 v24, v24, v75
	v_add_f32_e32 v25, v25, v75
	v_add_f32_e32 v26, v26, v75
	v_add_f32_e32 v27, v27, v75
	v_add_f32_e32 v114, v114, v84
	v_add_f32_e32 v115, v115, v84
	v_add_f32_e32 v116, v116, v84
	v_add_f32_e32 v117, v117, v84
	v_exp_f32_e32 v24, v24
	v_exp_f32_e32 v25, v25
	v_exp_f32_e32 v26, v26
	v_exp_f32_e32 v27, v27
	v_exp_f32_e32 v114, v114
	v_exp_f32_e32 v115, v115
	v_exp_f32_e32 v116, v116
	v_exp_f32_e32 v117, v117
	v_add_f32_e32 v24, 1.0, v24
	v_add_f32_e32 v25, 1.0, v25
	v_add_f32_e32 v26, 1.0, v26
	v_add_f32_e32 v27, 1.0, v27
	v_add_f32_e32 v114, 1.0, v114
	v_add_f32_e32 v115, 1.0, v115
	v_add_f32_e32 v116, 1.0, v116
	v_add_f32_e32 v117, 1.0, v117
	v_rcp_f32_e32 v24, v24
	v_rcp_f32_e32 v25, v25
	v_rcp_f32_e32 v26, v26
	v_rcp_f32_e32 v27, v27
	v_rcp_f32_e32 v114, v114
	v_rcp_f32_e32 v115, v115
	v_rcp_f32_e32 v116, v116
	v_rcp_f32_e32 v117, v117
	v_mul_f32_e32 v24, v85, v24
	v_mul_f32_e32 v25, v85, v25
	v_mul_f32_e32 v26, v85, v26
	v_mul_f32_e32 v27, v85, v27
	v_mul_f32_e32 v114, v114, v186
	v_mul_f32_e32 v115, v115, v187
	v_mul_f32_e32 v116, v116, v188
	v_mul_f32_e32 v117, v117, v189
	v_exp_f32_e32 v24, v24
	v_exp_f32_e32 v25, v25
	v_exp_f32_e32 v26, v26
	v_exp_f32_e32 v27, v27
	s_nop 0
	v_fma_f32 v138, -v24, v24, 1.0 clamp
	v_fma_f32 v139, -v25, v25, 1.0 clamp
	v_fma_f32 v140, -v26, v26, 1.0 clamp
	v_fma_f32 v141, -v27, v27, 1.0 clamp
	v_sqrt_f32_e32 v138, v138
	v_sqrt_f32_e32 v139, v139
	v_sqrt_f32_e32 v140, v140
	v_sqrt_f32_e32 v141, v141
	s_nop 0
	v_mul_f32_e32 v114, v138, v114
	v_mul_f32_e32 v115, v139, v115
	v_mul_f32_e32 v116, v140, v116
	v_mul_f32_e32 v117, v141, v117
	v_add_f32_e32 v28, v28, v75
	v_add_f32_e32 v29, v29, v75
	v_add_f32_e32 v30, v30, v75
	v_add_f32_e32 v31, v31, v75
	v_add_f32_e32 v118, v118, v84
	v_add_f32_e32 v119, v119, v84
	v_add_f32_e32 v120, v120, v84
	v_add_f32_e32 v121, v121, v84
	v_exp_f32_e32 v28, v28
	v_exp_f32_e32 v29, v29
	v_exp_f32_e32 v30, v30
	v_exp_f32_e32 v31, v31
	v_exp_f32_e32 v118, v118
	v_exp_f32_e32 v119, v119
	v_exp_f32_e32 v120, v120
	v_exp_f32_e32 v121, v121
	v_add_f32_e32 v28, 1.0, v28
	v_add_f32_e32 v29, 1.0, v29
	v_add_f32_e32 v30, 1.0, v30
	v_add_f32_e32 v31, 1.0, v31
	v_add_f32_e32 v118, 1.0, v118
	v_add_f32_e32 v119, 1.0, v119
	v_add_f32_e32 v120, 1.0, v120
	v_add_f32_e32 v121, 1.0, v121
	v_rcp_f32_e32 v28, v28
	v_rcp_f32_e32 v29, v29
	v_rcp_f32_e32 v30, v30
	v_rcp_f32_e32 v31, v31
	v_rcp_f32_e32 v118, v118
	v_rcp_f32_e32 v119, v119
	v_rcp_f32_e32 v120, v120
	v_rcp_f32_e32 v121, v121
	v_mul_f32_e32 v28, v85, v28
	v_mul_f32_e32 v29, v85, v29
	v_mul_f32_e32 v30, v85, v30
	v_mul_f32_e32 v31, v85, v31
	v_mul_f32_e32 v118, v118, v190
	v_mul_f32_e32 v119, v119, v191
	v_mul_f32_e32 v120, v120, v192
	v_mul_f32_e32 v121, v121, v193
	v_exp_f32_e32 v28, v28
	v_exp_f32_e32 v29, v29
	v_exp_f32_e32 v30, v30
	v_exp_f32_e32 v31, v31
	s_nop 0
	v_fma_f32 v138, -v28, v28, 1.0 clamp
	v_fma_f32 v139, -v29, v29, 1.0 clamp
	v_fma_f32 v140, -v30, v30, 1.0 clamp
	v_fma_f32 v141, -v31, v31, 1.0 clamp
	v_sqrt_f32_e32 v138, v138
	v_sqrt_f32_e32 v139, v139
	v_sqrt_f32_e32 v140, v140
	v_sqrt_f32_e32 v141, v141
	s_nop 0
	v_mul_f32_e32 v118, v138, v118
	v_mul_f32_e32 v119, v139, v119
	v_mul_f32_e32 v120, v140, v120
	v_mul_f32_e32 v121, v141, v121
	v_mov_b32_e32 v253, v0
	v_mov_b32_e32 v254, v90
	v_fma_f32 v254, v1, v254, v91
	v_mul_f32_e32 v253, v253, v1
	v_fma_f32 v254, v2, v254, v92
	v_mul_f32_e32 v253, v253, v2
	v_fma_f32 v254, v3, v254, v93
	v_mul_f32_e32 v253, v253, v3
	v_fma_f32 v254, v4, v254, v94
	v_mul_f32_e32 v253, v253, v4
	v_fma_f32 v254, v5, v254, v95
	v_mul_f32_e32 v253, v253, v5
	v_fma_f32 v254, v6, v254, v96
	v_mul_f32_e32 v253, v253, v6
	v_fma_f32 v254, v7, v254, v97
	v_mul_f32_e32 v253, v253, v7
	v_fma_f32 v254, v8, v254, v98
	v_mul_f32_e32 v253, v253, v8
	v_fma_f32 v254, v9, v254, v99
	v_mul_f32_e32 v253, v253, v9
	v_fma_f32 v254, v10, v254, v100
	v_mul_f32_e32 v253, v253, v10
	v_fma_f32 v254, v11, v254, v101
; __device__ __forceinline__ void lru_tile(const Params& P, int chunk, int head, int pass, char* smem_raw) {
;     ...
;       {
;         float Pp = 1.f, H = 0.f;
; #pragma unroll 4
;         for (int i = 0; i < 16; ++i) {
;           const int tl = (d == 0) ? (q * 16 + i) : (q * 16 + 15 - i);
;           const float a = sm_a[tl * 64 + ch], b = sm_b[tl * 64 + ch];
;           H = a * H + b; Pp *= a;
;         }
;         sm_ph[pos * 64 + ch] = make_float2(Pp, H);
;     ...
;       cB = p0.x * cB + p0.y; cA *= p0.x;
;       cB = p1.x * cB + p1.y; cA *= p1.x;
;       cB = p2.x * cB + p2.y; cA *= p2.x;
;       cB = p3.x * cB + p3.y; cA *= p3.x;
;       __syncthreads();
;     }
;     if (pass == 1 && q == 0) P.summ[((long)d * 264 + chunk) * 512 + gch] = make_float2(cA, cB);
	v_mul_f32_e32 v253, v253, v11
	v_fma_f32 v254, v12, v254, v102
	v_mul_f32_e32 v253, v253, v12
	v_fma_f32 v254, v13, v254, v103
	v_mul_f32_e32 v253, v253, v13
	v_fma_f32 v254, v14, v254, v104
	v_mul_f32_e32 v253, v253, v14
	v_fma_f32 v254, v15, v254, v105
	v_mul_f32_e32 v253, v253, v15
	v_fma_f32 v254, v16, v254, v106
	v_mul_f32_e32 v253, v253, v16
	v_fma_f32 v254, v17, v254, v107
	v_mul_f32_e32 v253, v253, v17
	v_fma_f32 v254, v18, v254, v108
	v_mul_f32_e32 v253, v253, v18
	v_fma_f32 v254, v19, v254, v109
	v_mul_f32_e32 v253, v253, v19
	v_fma_f32 v254, v20, v254, v110
	v_mul_f32_e32 v253, v253, v20
	v_fma_f32 v254, v21, v254, v111
	v_mul_f32_e32 v253, v253, v21
	v_fma_f32 v254, v22, v254, v112
	v_mul_f32_e32 v253, v253, v22
	v_fma_f32 v254, v23, v254, v113
	v_mul_f32_e32 v253, v253, v23
	v_fma_f32 v254, v24, v254, v114
	v_mul_f32_e32 v253, v253, v24
	v_fma_f32 v254, v25, v254, v115
	v_mul_f32_e32 v253, v253, v25
	v_fma_f32 v254, v26, v254, v116
	v_mul_f32_e32 v253, v253, v26
	v_fma_f32 v254, v27, v254, v117
	v_mul_f32_e32 v253, v253, v27
	v_fma_f32 v254, v28, v254, v118
	v_mul_f32_e32 v253, v253, v28
	v_fma_f32 v254, v29, v254, v119
	v_mul_f32_e32 v253, v253, v29
	v_fma_f32 v254, v30, v254, v120
	v_mul_f32_e32 v253, v253, v30
	v_fma_f32 v254, v31, v254, v121
	v_mul_f32_e32 v253, v253, v31
	v_mov_b32_e32 v138, v253
	v_mov_b32_e32 v139, v253
	s_nop 1
	v_permlane16_swap_b32_e32 v138, v139
	v_mov_b32_e32 v140, v138
	v_mov_b32_e32 v141, v139
	s_nop 1
	v_permlane32_swap_b32_e32 v138, v140
	v_permlane32_swap_b32_e32 v139, v141
	v_mov_b32_e32 v198, v254
	v_mov_b32_e32 v199, v254
	s_nop 1
	v_permlane16_swap_b32_e32 v198, v199
	v_mov_b32_e32 v200, v198
	v_mov_b32_e32 v201, v199
	s_nop 1
	v_permlane32_swap_b32_e32 v198, v200
	v_permlane32_swap_b32_e32 v199, v201
	v_mov_b32_e32 v136, 0
	v_fma_f32 v150, v138, v136, v198
	v_fma_f32 v151, v139, v150, v199
	v_fma_f32 v202, v140, v151, v200
	v_fma_f32 v254, v141, v202, v201
	v_mul_f32_e32 v253, v138, v139
	v_mul_f32_e32 v253, v253, v140
	v_mul_f32_e32 v200, v253, v141
	v_mov_b32_e32 v201, v254
	s_add_u32 s0, s71, 0
	s_lshl_b32 s0, s0, 12
	s_lshl_b32 s1, s56, 3
	s_add_u32 s0, s0, s1
	s_add_u32 s4, s18, s0
	s_addc_u32 s5, s19, 0
	global_store_dwordx2 v250, v[200:201], s[4:5]
	ds_read_b128 v[76:79], v131 offset:0
	ds_read_b128 v[80:83], v133 offset:0
	ds_read_b128 v[122:125], v131 offset:512
	ds_read_b128 v[126:129], v133 offset:512
	s_waitcnt vmcnt(1)
	s_waitcnt lgkmcnt(3)
	v_mfma_f32_16x16x32_bf16 v[0:3], v[76:79], v[238:241], 0
	v_mfma_f32_16x16x32_bf16 v[90:93], v[76:79], v[246:249], 0
	ds_read_b128 v[76:79], v131 offset:1024
	s_waitcnt lgkmcnt(3)
	v_mfma_f32_16x16x32_bf16 v[0:3], v[80:83], v[242:245], v[0:3]
	v_mfma_f32_16x16x32_bf16 v[90:93], v[80:83], v[194:197], v[90:93]
	ds_read_b128 v[80:83], v133 offset:1024
	s_waitcnt lgkmcnt(3)
	v_mfma_f32_16x16x32_bf16 v[4:7], v[122:125], v[238:241], 0
	v_mfma_f32_16x16x32_bf16 v[94:97], v[122:125], v[246:249], 0
	ds_read_b128 v[122:125], v131 offset:1536
	s_waitcnt lgkmcnt(3)
	v_mfma_f32_16x16x32_bf16 v[4:7], v[126:129], v[242:245], v[4:7]
	v_mfma_f32_16x16x32_bf16 v[94:97], v[126:129], v[194:197], v[94:97]
	ds_read_b128 v[126:129], v133 offset:1536
	s_waitcnt lgkmcnt(3)
	v_mfma_f32_16x16x32_bf16 v[8:11], v[76:79], v[238:241], 0
	v_mfma_f32_16x16x32_bf16 v[98:101], v[76:79], v[246:249], 0
	ds_read_b128 v[76:79], v131 offset:2048
	s_waitcnt lgkmcnt(3)
	v_mfma_f32_16x16x32_bf16 v[8:11], v[80:83], v[242:245], v[8:11]
	v_mfma_f32_16x16x32_bf16 v[98:101], v[80:83], v[194:197], v[98:101]
	ds_read_b128 v[80:83], v133 offset:2048
	s_waitcnt lgkmcnt(3)
	v_mfma_f32_16x16x32_bf16 v[12:15], v[122:125], v[238:241], 0
	v_mfma_f32_16x16x32_bf16 v[102:105], v[122:125], v[246:249], 0
	ds_read_b128 v[122:125], v131 offset:2560
	s_waitcnt lgkmcnt(3)
	v_mfma_f32_16x16x32_bf16 v[12:15], v[126:129], v[242:245], v[12:15]
	v_mfma_f32_16x16x32_bf16 v[102:105], v[126:129], v[194:197], v[102:105]
	ds_read_b128 v[126:129], v133 offset:2560
	s_waitcnt lgkmcnt(3)
	v_mfma_f32_16x16x32_bf16 v[16:19], v[76:79], v[238:241], 0
	v_mfma_f32_16x16x32_bf16 v[106:109], v[76:79], v[246:249], 0
	ds_read_b128 v[76:79], v131 offset:3072
	s_waitcnt lgkmcnt(3)
	v_mfma_f32_16x16x32_bf16 v[16:19], v[80:83], v[242:245], v[16:19]
	v_mfma_f32_16x16x32_bf16 v[106:109], v[80:83], v[194:197], v[106:109]
	ds_read_b128 v[80:83], v133 offset:3072
	s_waitcnt lgkmcnt(3)
	v_mfma_f32_16x16x32_bf16 v[20:23], v[122:125], v[238:241], 0
	v_mfma_f32_16x16x32_bf16 v[110:113], v[122:125], v[246:249], 0
	ds_read_b128 v[122:125], v131 offset:3584
	s_waitcnt lgkmcnt(3)
	v_mfma_f32_16x16x32_bf16 v[20:23], v[126:129], v[242:245], v[20:23]
	v_mfma_f32_16x16x32_bf16 v[110:113], v[126:129], v[194:197], v[110:113]
	ds_read_b128 v[126:129], v133 offset:3584
	s_waitcnt lgkmcnt(3)
	v_mfma_f32_16x16x32_bf16 v[24:27], v[76:79], v[238:241], 0
	v_mfma_f32_16x16x32_bf16 v[114:117], v[76:79], v[246:249], 0
	s_waitcnt lgkmcnt(2)
	v_mfma_f32_16x16x32_bf16 v[24:27], v[80:83], v[242:245], v[24:27]
	v_mfma_f32_16x16x32_bf16 v[114:117], v[80:83], v[194:197], v[114:117]
	s_waitcnt lgkmcnt(1)
	v_mfma_f32_16x16x32_bf16 v[28:31], v[122:125], v[238:241], 0
	v_mfma_f32_16x16x32_bf16 v[118:121], v[122:125], v[246:249], 0
	s_waitcnt lgkmcnt(0)
; __device__ __forceinline__ float bf2f(u16 h) { return __uint_as_float(((unsigned)h) << 16); }
; __device__ __forceinline__ void lru_tile(const Params& P, int chunk, int head, int pass, char* smem_raw) {
;     ...
;       for (int s = 0; s < 2; ++s) {
;         const bf16x8 af = *reinterpret_cast<const bf16x8*>(&sm_uc[(sb * 64 + wid * 16 + (lane & 15)) * LDSS + s * 32 + (lane >> 4) * 8]);
; #pragma unroll
;         for (int t = 0; t < 8; ++t) {
;           const bf16x8 bfr = *reinterpret_cast<const bf16x8*>(&sm_w[(t * 16 + (lane & 15)) * LDSS + s * 32 + (lane >> 4) * 8]);
;           acc[t] = __builtin_amdgcn_mfma_f32_16x16x32_bf16(af, bfr, acc[t], 0, 0, 0);
;         }
;       }
; #pragma unroll
;       for (int tc = 0; tc < 4; ++tc)
; #pragma unroll
;         for (int reg = 0; reg < 4; ++reg) {
;           const int tl = wid * 16 + (lane >> 4) * 4 + reg;
;           const int c = 16 * tc + (lane & 15);
;           const float r = __builtin_amdgcn_rcpf(1.f + __builtin_amdgcn_exp2f(acc[tc][reg] + ba[tc]));
;           const float ii = __builtin_amdgcn_rcpf(1.f + __builtin_amdgcn_exp2f(acc[tc + 4][reg] + bi[tc]));
;           const float la = -c8[tc] * r;
;           const float a = __builtin_amdgcn_exp2f(la);
;           const float ucv = bf2f(sm_uc[(sb * 64 + tl) * LDSS + c]);
;           const float bt = __builtin_amdgcn_sqrtf(fmaxf(1.f - a * a, 0.f)) * (ii * ucv);
;           sm_a[tl * 64 + c] = a;
;           sm_b[tl * 64 + c] = bt;
;         }
	v_mfma_f32_16x16x32_bf16 v[28:31], v[126:129], v[242:245], v[28:31]
	v_mfma_f32_16x16x32_bf16 v[118:121], v[126:129], v[194:197], v[118:121]
	s_lshl_b32 s0, s56, 8
	s_add_u32 s0, s0, 0x0
	s_add_u32 s4, s20, s0
	s_addc_u32 s5, s21, 0
	global_load_dwordx4 v[238:241], v251, s[4:5]
	global_load_dwordx4 v[242:245], v251, s[4:5] offset:64
	s_add_u32 s4, s4, 0x2000
	s_addc_u32 s5, s5, 0
	global_load_dwordx4 v[246:249], v251, s[4:5]
	global_load_dwordx4 v[194:197], v251, s[4:5] offset:64
	s_nop 7
	s_nop 7
	v_add_f32_e32 v0, v0, v145
	v_add_f32_e32 v1, v1, v145
	v_add_f32_e32 v2, v2, v145
	v_add_f32_e32 v3, v3, v145
	v_add_f32_e32 v90, v90, v146
	v_add_f32_e32 v91, v91, v146
	v_add_f32_e32 v92, v92, v146
	v_add_f32_e32 v93, v93, v146
	v_exp_f32_e32 v0, v0
	v_exp_f32_e32 v1, v1
	v_exp_f32_e32 v2, v2
	v_exp_f32_e32 v3, v3
	v_exp_f32_e32 v90, v90
	v_exp_f32_e32 v91, v91
	v_exp_f32_e32 v92, v92
	v_exp_f32_e32 v93, v93
	v_add_f32_e32 v0, 1.0, v0
	v_add_f32_e32 v1, 1.0, v1
	v_add_f32_e32 v2, 1.0, v2
	v_add_f32_e32 v3, 1.0, v3
	v_add_f32_e32 v90, 1.0, v90
	v_add_f32_e32 v91, 1.0, v91
	v_add_f32_e32 v92, 1.0, v92
	v_add_f32_e32 v93, 1.0, v93
	v_rcp_f32_e32 v0, v0
	v_rcp_f32_e32 v1, v1
	v_rcp_f32_e32 v2, v2
	v_rcp_f32_e32 v3, v3
	v_rcp_f32_e32 v90, v90
	v_rcp_f32_e32 v91, v91
	v_rcp_f32_e32 v92, v92
	v_rcp_f32_e32 v93, v93
	v_mul_f32_e32 v0, v147, v0
	v_mul_f32_e32 v1, v147, v1
	v_mul_f32_e32 v2, v147, v2
	v_mul_f32_e32 v3, v147, v3
	v_mul_f32_e32 v90, v90, v162
	v_mul_f32_e32 v91, v91, v163
	v_mul_f32_e32 v92, v92, v164
	v_mul_f32_e32 v93, v93, v165
	v_exp_f32_e32 v0, v0
	v_exp_f32_e32 v1, v1
	v_exp_f32_e32 v2, v2
	v_exp_f32_e32 v3, v3
	s_nop 0
	v_fma_f32 v138, -v0, v0, 1.0 clamp
	v_fma_f32 v139, -v1, v1, 1.0 clamp
	v_fma_f32 v140, -v2, v2, 1.0 clamp
	v_fma_f32 v141, -v3, v3, 1.0 clamp
	v_sqrt_f32_e32 v138, v138
	v_sqrt_f32_e32 v139, v139
	v_sqrt_f32_e32 v140, v140
	v_sqrt_f32_e32 v141, v141
	s_nop 0
	v_mul_f32_e32 v90, v138, v90
	v_mul_f32_e32 v91, v139, v91
	v_mul_f32_e32 v92, v140, v92
	v_mul_f32_e32 v93, v141, v93
	v_add_f32_e32 v4, v4, v145
	v_add_f32_e32 v5, v5, v145
	v_add_f32_e32 v6, v6, v145
	v_add_f32_e32 v7, v7, v145
	v_add_f32_e32 v94, v94, v146
	v_add_f32_e32 v95, v95, v146
	v_add_f32_e32 v96, v96, v146
	v_add_f32_e32 v97, v97, v146
	v_exp_f32_e32 v4, v4
	v_exp_f32_e32 v5, v5
	v_exp_f32_e32 v6, v6
	v_exp_f32_e32 v7, v7
	v_exp_f32_e32 v94, v94
	v_exp_f32_e32 v95, v95
	v_exp_f32_e32 v96, v96
	v_exp_f32_e32 v97, v97
	v_add_f32_e32 v4, 1.0, v4
	v_add_f32_e32 v5, 1.0, v5
	v_add_f32_e32 v6, 1.0, v6
	v_add_f32_e32 v7, 1.0, v7
	v_add_f32_e32 v94, 1.0, v94
	v_add_f32_e32 v95, 1.0, v95
	v_add_f32_e32 v96, 1.0, v96
	v_add_f32_e32 v97, 1.0, v97
	v_rcp_f32_e32 v4, v4
	v_rcp_f32_e32 v5, v5
	v_rcp_f32_e32 v6, v6
	v_rcp_f32_e32 v7, v7
	v_rcp_f32_e32 v94, v94
	v_rcp_f32_e32 v95, v95
	v_rcp_f32_e32 v96, v96
	v_rcp_f32_e32 v97, v97
	v_mul_f32_e32 v4, v147, v4
	v_mul_f32_e32 v5, v147, v5
	v_mul_f32_e32 v6, v147, v6
	v_mul_f32_e32 v7, v147, v7
	v_mul_f32_e32 v94, v94, v166
	v_mul_f32_e32 v95, v95, v167
	v_mul_f32_e32 v96, v96, v168
	v_mul_f32_e32 v97, v97, v169
	v_exp_f32_e32 v4, v4
	v_exp_f32_e32 v5, v5
	v_exp_f32_e32 v6, v6
	v_exp_f32_e32 v7, v7
	s_nop 0
	v_fma_f32 v138, -v4, v4, 1.0 clamp
	v_fma_f32 v139, -v5, v5, 1.0 clamp
	v_fma_f32 v140, -v6, v6, 1.0 clamp
	v_fma_f32 v141, -v7, v7, 1.0 clamp
	v_sqrt_f32_e32 v138, v138
	v_sqrt_f32_e32 v139, v139
	v_sqrt_f32_e32 v140, v140
	v_sqrt_f32_e32 v141, v141
	s_nop 0
	v_mul_f32_e32 v94, v138, v94
	v_mul_f32_e32 v95, v139, v95
	v_mul_f32_e32 v96, v140, v96
	v_mul_f32_e32 v97, v141, v97
	v_add_f32_e32 v8, v8, v145
	v_add_f32_e32 v9, v9, v145
	v_add_f32_e32 v10, v10, v145
	v_add_f32_e32 v11, v11, v145
	v_add_f32_e32 v98, v98, v146
	v_add_f32_e32 v99, v99, v146
	v_add_f32_e32 v100, v100, v146
	v_add_f32_e32 v101, v101, v146
	v_exp_f32_e32 v8, v8
	v_exp_f32_e32 v9, v9
	v_exp_f32_e32 v10, v10
	v_exp_f32_e32 v11, v11
	v_exp_f32_e32 v98, v98
	v_exp_f32_e32 v99, v99
	v_exp_f32_e32 v100, v100
	v_exp_f32_e32 v101, v101
	v_add_f32_e32 v8, 1.0, v8
	v_add_f32_e32 v9, 1.0, v9
	v_add_f32_e32 v10, 1.0, v10
	v_add_f32_e32 v11, 1.0, v11
	v_add_f32_e32 v98, 1.0, v98
	v_add_f32_e32 v99, 1.0, v99
	v_add_f32_e32 v100, 1.0, v100
	v_add_f32_e32 v101, 1.0, v101
	v_rcp_f32_e32 v8, v8
	v_rcp_f32_e32 v9, v9
	v_rcp_f32_e32 v10, v10
	v_rcp_f32_e32 v11, v11
	v_rcp_f32_e32 v98, v98
	v_rcp_f32_e32 v99, v99
	v_rcp_f32_e32 v100, v100
	v_rcp_f32_e32 v101, v101
	v_mul_f32_e32 v8, v147, v8
	v_mul_f32_e32 v9, v147, v9
	v_mul_f32_e32 v10, v147, v10
	v_mul_f32_e32 v11, v147, v11
	v_mul_f32_e32 v98, v98, v170
	v_mul_f32_e32 v99, v99, v171
	v_mul_f32_e32 v100, v100, v172
	v_mul_f32_e32 v101, v101, v173
	v_exp_f32_e32 v8, v8
	v_exp_f32_e32 v9, v9
	v_exp_f32_e32 v10, v10
	v_exp_f32_e32 v11, v11
	s_nop 0
	v_fma_f32 v138, -v8, v8, 1.0 clamp
	v_fma_f32 v139, -v9, v9, 1.0 clamp
	v_fma_f32 v140, -v10, v10, 1.0 clamp
	v_fma_f32 v141, -v11, v11, 1.0 clamp
	v_sqrt_f32_e32 v138, v138
	v_sqrt_f32_e32 v139, v139
	v_sqrt_f32_e32 v140, v140
	v_sqrt_f32_e32 v141, v141
	s_nop 0
	v_mul_f32_e32 v98, v138, v98
	v_mul_f32_e32 v99, v139, v99
	v_mul_f32_e32 v100, v140, v100
	v_mul_f32_e32 v101, v141, v101
	v_add_f32_e32 v12, v12, v145
	v_add_f32_e32 v13, v13, v145
	v_add_f32_e32 v14, v14, v145
	v_add_f32_e32 v15, v15, v145
	v_add_f32_e32 v102, v102, v146
	v_add_f32_e32 v103, v103, v146
	v_add_f32_e32 v104, v104, v146
	v_add_f32_e32 v105, v105, v146
	v_exp_f32_e32 v12, v12
	v_exp_f32_e32 v13, v13
	v_exp_f32_e32 v14, v14
	v_exp_f32_e32 v15, v15
	v_exp_f32_e32 v102, v102
	v_exp_f32_e32 v103, v103
	v_exp_f32_e32 v104, v104
	v_exp_f32_e32 v105, v105
	v_add_f32_e32 v12, 1.0, v12
; __device__ __forceinline__ float bf2f(u16 h) { return __uint_as_float(((unsigned)h) << 16); }
; __device__ __forceinline__ void lru_tile(const Params& P, int chunk, int head, int pass, char* smem_raw) {
;     ...
;       for (int tc = 0; tc < 4; ++tc)
; #pragma unroll
;         for (int reg = 0; reg < 4; ++reg) {
;           const int tl = wid * 16 + (lane >> 4) * 4 + reg;
;           const int c = 16 * tc + (lane & 15);
;           const float r = __builtin_amdgcn_rcpf(1.f + __builtin_amdgcn_exp2f(acc[tc][reg] + ba[tc]));
;           const float ii = __builtin_amdgcn_rcpf(1.f + __builtin_amdgcn_exp2f(acc[tc + 4][reg] + bi[tc]));
;           const float la = -c8[tc] * r;
;           const float a = __builtin_amdgcn_exp2f(la);
;           const float ucv = bf2f(sm_uc[(sb * 64 + tl) * LDSS + c]);
;           const float bt = __builtin_amdgcn_sqrtf(fmaxf(1.f - a * a, 0.f)) * (ii * ucv);
;           sm_a[tl * 64 + c] = a;
;           sm_b[tl * 64 + c] = bt;
;         }
	v_add_f32_e32 v13, 1.0, v13
	v_add_f32_e32 v14, 1.0, v14
	v_add_f32_e32 v15, 1.0, v15
	v_add_f32_e32 v102, 1.0, v102
	v_add_f32_e32 v103, 1.0, v103
	v_add_f32_e32 v104, 1.0, v104
	v_add_f32_e32 v105, 1.0, v105
	v_rcp_f32_e32 v12, v12
	v_rcp_f32_e32 v13, v13
	v_rcp_f32_e32 v14, v14
	v_rcp_f32_e32 v15, v15
	v_rcp_f32_e32 v102, v102
	v_rcp_f32_e32 v103, v103
	v_rcp_f32_e32 v104, v104
	v_rcp_f32_e32 v105, v105
	v_mul_f32_e32 v12, v147, v12
	v_mul_f32_e32 v13, v147, v13
	v_mul_f32_e32 v14, v147, v14
	v_mul_f32_e32 v15, v147, v15
	v_mul_f32_e32 v102, v102, v174
	v_mul_f32_e32 v103, v103, v175
	v_mul_f32_e32 v104, v104, v176
	v_mul_f32_e32 v105, v105, v177
	v_exp_f32_e32 v12, v12
	v_exp_f32_e32 v13, v13
	v_exp_f32_e32 v14, v14
	v_exp_f32_e32 v15, v15
	s_nop 0
	v_fma_f32 v138, -v12, v12, 1.0 clamp
	v_fma_f32 v139, -v13, v13, 1.0 clamp
	v_fma_f32 v140, -v14, v14, 1.0 clamp
	v_fma_f32 v141, -v15, v15, 1.0 clamp
	v_sqrt_f32_e32 v138, v138
	v_sqrt_f32_e32 v139, v139
	v_sqrt_f32_e32 v140, v140
	v_sqrt_f32_e32 v141, v141
	s_nop 0
	v_mul_f32_e32 v102, v138, v102
	v_mul_f32_e32 v103, v139, v103
	v_mul_f32_e32 v104, v140, v104
	v_mul_f32_e32 v105, v141, v105
	v_add_f32_e32 v16, v16, v145
	v_add_f32_e32 v17, v17, v145
	v_add_f32_e32 v18, v18, v145
	v_add_f32_e32 v19, v19, v145
	v_add_f32_e32 v106, v106, v146
	v_add_f32_e32 v107, v107, v146
	v_add_f32_e32 v108, v108, v146
	v_add_f32_e32 v109, v109, v146
	v_exp_f32_e32 v16, v16
	v_exp_f32_e32 v17, v17
	v_exp_f32_e32 v18, v18
	v_exp_f32_e32 v19, v19
	v_exp_f32_e32 v106, v106
	v_exp_f32_e32 v107, v107
	v_exp_f32_e32 v108, v108
	v_exp_f32_e32 v109, v109
	v_add_f32_e32 v16, 1.0, v16
	v_add_f32_e32 v17, 1.0, v17
	v_add_f32_e32 v18, 1.0, v18
	v_add_f32_e32 v19, 1.0, v19
	v_add_f32_e32 v106, 1.0, v106
	v_add_f32_e32 v107, 1.0, v107
	v_add_f32_e32 v108, 1.0, v108
	v_add_f32_e32 v109, 1.0, v109
	v_rcp_f32_e32 v16, v16
	v_rcp_f32_e32 v17, v17
	v_rcp_f32_e32 v18, v18
	v_rcp_f32_e32 v19, v19
	v_rcp_f32_e32 v106, v106
	v_rcp_f32_e32 v107, v107
	v_rcp_f32_e32 v108, v108
	v_rcp_f32_e32 v109, v109
	v_mul_f32_e32 v16, v147, v16
	v_mul_f32_e32 v17, v147, v17
	v_mul_f32_e32 v18, v147, v18
	v_mul_f32_e32 v19, v147, v19
	v_mul_f32_e32 v106, v106, v178
	v_mul_f32_e32 v107, v107, v179
	v_mul_f32_e32 v108, v108, v180
	v_mul_f32_e32 v109, v109, v181
	v_exp_f32_e32 v16, v16
	v_exp_f32_e32 v17, v17
	v_exp_f32_e32 v18, v18
	v_exp_f32_e32 v19, v19
	s_nop 0
	v_fma_f32 v138, -v16, v16, 1.0 clamp
	v_fma_f32 v139, -v17, v17, 1.0 clamp
	v_fma_f32 v140, -v18, v18, 1.0 clamp
	v_fma_f32 v141, -v19, v19, 1.0 clamp
	v_sqrt_f32_e32 v138, v138
	v_sqrt_f32_e32 v139, v139
	v_sqrt_f32_e32 v140, v140
	v_sqrt_f32_e32 v141, v141
	s_nop 0
	v_mul_f32_e32 v106, v138, v106
	v_mul_f32_e32 v107, v139, v107
	v_mul_f32_e32 v108, v140, v108
	v_mul_f32_e32 v109, v141, v109
	v_add_f32_e32 v20, v20, v145
	v_add_f32_e32 v21, v21, v145
	v_add_f32_e32 v22, v22, v145
	v_add_f32_e32 v23, v23, v145
	v_add_f32_e32 v110, v110, v146
	v_add_f32_e32 v111, v111, v146
	v_add_f32_e32 v112, v112, v146
	v_add_f32_e32 v113, v113, v146
	v_exp_f32_e32 v20, v20
	v_exp_f32_e32 v21, v21
	v_exp_f32_e32 v22, v22
	v_exp_f32_e32 v23, v23
	v_exp_f32_e32 v110, v110
	v_exp_f32_e32 v111, v111
	v_exp_f32_e32 v112, v112
	v_exp_f32_e32 v113, v113
	v_add_f32_e32 v20, 1.0, v20
	v_add_f32_e32 v21, 1.0, v21
	v_add_f32_e32 v22, 1.0, v22
	v_add_f32_e32 v23, 1.0, v23
	v_add_f32_e32 v110, 1.0, v110
	v_add_f32_e32 v111, 1.0, v111
	v_add_f32_e32 v112, 1.0, v112
	v_add_f32_e32 v113, 1.0, v113
	v_rcp_f32_e32 v20, v20
	v_rcp_f32_e32 v21, v21
	v_rcp_f32_e32 v22, v22
	v_rcp_f32_e32 v23, v23
	v_rcp_f32_e32 v110, v110
	v_rcp_f32_e32 v111, v111
	v_rcp_f32_e32 v112, v112
	v_rcp_f32_e32 v113, v113
	v_mul_f32_e32 v20, v147, v20
	v_mul_f32_e32 v21, v147, v21
	v_mul_f32_e32 v22, v147, v22
	v_mul_f32_e32 v23, v147, v23
	v_mul_f32_e32 v110, v110, v182
	v_mul_f32_e32 v111, v111, v183
	v_mul_f32_e32 v112, v112, v184
	v_mul_f32_e32 v113, v113, v185
	v_exp_f32_e32 v20, v20
	v_exp_f32_e32 v21, v21
	v_exp_f32_e32 v22, v22
	v_exp_f32_e32 v23, v23
	s_nop 0
	v_fma_f32 v138, -v20, v20, 1.0 clamp
	v_fma_f32 v139, -v21, v21, 1.0 clamp
	v_fma_f32 v140, -v22, v22, 1.0 clamp
	v_fma_f32 v141, -v23, v23, 1.0 clamp
	v_sqrt_f32_e32 v138, v138
	v_sqrt_f32_e32 v139, v139
	v_sqrt_f32_e32 v140, v140
	v_sqrt_f32_e32 v141, v141
	s_nop 0
	v_mul_f32_e32 v110, v138, v110
	v_mul_f32_e32 v111, v139, v111
	v_mul_f32_e32 v112, v140, v112
	v_mul_f32_e32 v113, v141, v113
	v_add_f32_e32 v24, v24, v145
	v_add_f32_e32 v25, v25, v145
	v_add_f32_e32 v26, v26, v145
	v_add_f32_e32 v27, v27, v145
	v_add_f32_e32 v114, v114, v146
	v_add_f32_e32 v115, v115, v146
	v_add_f32_e32 v116, v116, v146
	v_add_f32_e32 v117, v117, v146
	v_exp_f32_e32 v24, v24
	v_exp_f32_e32 v25, v25
	v_exp_f32_e32 v26, v26
	v_exp_f32_e32 v27, v27
	v_exp_f32_e32 v114, v114
	v_exp_f32_e32 v115, v115
	v_exp_f32_e32 v116, v116
	v_exp_f32_e32 v117, v117
	v_add_f32_e32 v24, 1.0, v24
	v_add_f32_e32 v25, 1.0, v25
	v_add_f32_e32 v26, 1.0, v26
	v_add_f32_e32 v27, 1.0, v27
	v_add_f32_e32 v114, 1.0, v114
	v_add_f32_e32 v115, 1.0, v115
	v_add_f32_e32 v116, 1.0, v116
	v_add_f32_e32 v117, 1.0, v117
	v_rcp_f32_e32 v24, v24
	v_rcp_f32_e32 v25, v25
	v_rcp_f32_e32 v26, v26
	v_rcp_f32_e32 v27, v27
	v_rcp_f32_e32 v114, v114
	v_rcp_f32_e32 v115, v115
	v_rcp_f32_e32 v116, v116
	v_rcp_f32_e32 v117, v117
	v_mul_f32_e32 v24, v147, v24
	v_mul_f32_e32 v25, v147, v25
; __device__ __forceinline__ float bf2f(u16 h) { return __uint_as_float(((unsigned)h) << 16); }
; __device__ __forceinline__ void lru_tile(const Params& P, int chunk, int head, int pass, char* smem_raw) {
;     ...
;       for (int tc = 0; tc < 4; ++tc)
; #pragma unroll
;         for (int reg = 0; reg < 4; ++reg) {
;           const int tl = wid * 16 + (lane >> 4) * 4 + reg;
;           const int c = 16 * tc + (lane & 15);
;           const float r = __builtin_amdgcn_rcpf(1.f + __builtin_amdgcn_exp2f(acc[tc][reg] + ba[tc]));
;           const float ii = __builtin_amdgcn_rcpf(1.f + __builtin_amdgcn_exp2f(acc[tc + 4][reg] + bi[tc]));
;           const float la = -c8[tc] * r;
;           const float a = __builtin_amdgcn_exp2f(la);
;           const float ucv = bf2f(sm_uc[(sb * 64 + tl) * LDSS + c]);
;           const float bt = __builtin_amdgcn_sqrtf(fmaxf(1.f - a * a, 0.f)) * (ii * ucv);
;           sm_a[tl * 64 + c] = a;
;           sm_b[tl * 64 + c] = bt;
;         }
;       __syncthreads();
;       const int pos = (d == 0) ? q : 3 - q;
;       {
;         float Pp = 1.f, H = 0.f;
; #pragma unroll 4
;         for (int i = 0; i < 16; ++i) {
;           const int tl = (d == 0) ? (q * 16 + i) : (q * 16 + 15 - i);
;           const float a = sm_a[tl * 64 + ch], b = sm_b[tl * 64 + ch];
;           H = a * H + b; Pp *= a;
;         }
;         sm_ph[pos * 64 + ch] = make_float2(Pp, H);
;     ...
;       cB = p0.x * cB + p0.y; cA *= p0.x;
;       cB = p1.x * cB + p1.y; cA *= p1.x;
;       cB = p2.x * cB + p2.y; cA *= p2.x;
;       cB = p3.x * cB + p3.y; cA *= p3.x;
;       __syncthreads();
;     }
;     if (pass == 1 && q == 0) P.summ[((long)d * 264 + chunk) * 512 + gch] = make_float2(cA, cB);
	v_mul_f32_e32 v26, v147, v26
	v_mul_f32_e32 v27, v147, v27
	v_mul_f32_e32 v114, v114, v186
	v_mul_f32_e32 v115, v115, v187
	v_mul_f32_e32 v116, v116, v188
	v_mul_f32_e32 v117, v117, v189
	v_exp_f32_e32 v24, v24
	v_exp_f32_e32 v25, v25
	v_exp_f32_e32 v26, v26
	v_exp_f32_e32 v27, v27
	s_nop 0
	v_fma_f32 v138, -v24, v24, 1.0 clamp
	v_fma_f32 v139, -v25, v25, 1.0 clamp
	v_fma_f32 v140, -v26, v26, 1.0 clamp
	v_fma_f32 v141, -v27, v27, 1.0 clamp
	v_sqrt_f32_e32 v138, v138
	v_sqrt_f32_e32 v139, v139
	v_sqrt_f32_e32 v140, v140
	v_sqrt_f32_e32 v141, v141
	s_nop 0
	v_mul_f32_e32 v114, v138, v114
	v_mul_f32_e32 v115, v139, v115
	v_mul_f32_e32 v116, v140, v116
	v_mul_f32_e32 v117, v141, v117
	v_add_f32_e32 v28, v28, v145
	v_add_f32_e32 v29, v29, v145
	v_add_f32_e32 v30, v30, v145
	v_add_f32_e32 v31, v31, v145
	v_add_f32_e32 v118, v118, v146
	v_add_f32_e32 v119, v119, v146
	v_add_f32_e32 v120, v120, v146
	v_add_f32_e32 v121, v121, v146
	v_exp_f32_e32 v28, v28
	v_exp_f32_e32 v29, v29
	v_exp_f32_e32 v30, v30
	v_exp_f32_e32 v31, v31
	v_exp_f32_e32 v118, v118
	v_exp_f32_e32 v119, v119
	v_exp_f32_e32 v120, v120
	v_exp_f32_e32 v121, v121
	v_add_f32_e32 v28, 1.0, v28
	v_add_f32_e32 v29, 1.0, v29
	v_add_f32_e32 v30, 1.0, v30
	v_add_f32_e32 v31, 1.0, v31
	v_add_f32_e32 v118, 1.0, v118
	v_add_f32_e32 v119, 1.0, v119
	v_add_f32_e32 v120, 1.0, v120
	v_add_f32_e32 v121, 1.0, v121
	v_rcp_f32_e32 v28, v28
	v_rcp_f32_e32 v29, v29
	v_rcp_f32_e32 v30, v30
	v_rcp_f32_e32 v31, v31
	v_rcp_f32_e32 v118, v118
	v_rcp_f32_e32 v119, v119
	v_rcp_f32_e32 v120, v120
	v_rcp_f32_e32 v121, v121
	v_mul_f32_e32 v28, v147, v28
	v_mul_f32_e32 v29, v147, v29
	v_mul_f32_e32 v30, v147, v30
	v_mul_f32_e32 v31, v147, v31
	v_mul_f32_e32 v118, v118, v190
	v_mul_f32_e32 v119, v119, v191
	v_mul_f32_e32 v120, v120, v192
	v_mul_f32_e32 v121, v121, v193
	v_exp_f32_e32 v28, v28
	v_exp_f32_e32 v29, v29
	v_exp_f32_e32 v30, v30
	v_exp_f32_e32 v31, v31
	s_nop 0
	v_fma_f32 v138, -v28, v28, 1.0 clamp
	v_fma_f32 v139, -v29, v29, 1.0 clamp
	v_fma_f32 v140, -v30, v30, 1.0 clamp
	v_fma_f32 v141, -v31, v31, 1.0 clamp
	v_sqrt_f32_e32 v138, v138
	v_sqrt_f32_e32 v139, v139
	v_sqrt_f32_e32 v140, v140
	v_sqrt_f32_e32 v141, v141
	s_nop 0
	v_mul_f32_e32 v118, v138, v118
	v_mul_f32_e32 v119, v139, v119
	v_mul_f32_e32 v120, v140, v120
	v_mul_f32_e32 v121, v141, v121
	v_mov_b32_e32 v253, v31
	v_mov_b32_e32 v254, v121
	v_fma_f32 v254, v30, v254, v120
	v_mul_f32_e32 v253, v253, v30
	v_fma_f32 v254, v29, v254, v119
	v_mul_f32_e32 v253, v253, v29
	v_fma_f32 v254, v28, v254, v118
	v_mul_f32_e32 v253, v253, v28
	v_fma_f32 v254, v27, v254, v117
	v_mul_f32_e32 v253, v253, v27
	v_fma_f32 v254, v26, v254, v116
	v_mul_f32_e32 v253, v253, v26
	v_fma_f32 v254, v25, v254, v115
	v_mul_f32_e32 v253, v253, v25
	v_fma_f32 v254, v24, v254, v114
	v_mul_f32_e32 v253, v253, v24
	v_fma_f32 v254, v23, v254, v113
	v_mul_f32_e32 v253, v253, v23
	v_fma_f32 v254, v22, v254, v112
	v_mul_f32_e32 v253, v253, v22
	v_fma_f32 v254, v21, v254, v111
	v_mul_f32_e32 v253, v253, v21
	v_fma_f32 v254, v20, v254, v110
	v_mul_f32_e32 v253, v253, v20
	v_fma_f32 v254, v19, v254, v109
	v_mul_f32_e32 v253, v253, v19
	v_fma_f32 v254, v18, v254, v108
	v_mul_f32_e32 v253, v253, v18
	v_fma_f32 v254, v17, v254, v107
	v_mul_f32_e32 v253, v253, v17
	v_fma_f32 v254, v16, v254, v106
	v_mul_f32_e32 v253, v253, v16
	v_fma_f32 v254, v15, v254, v105
	v_mul_f32_e32 v253, v253, v15
	v_fma_f32 v254, v14, v254, v104
	v_mul_f32_e32 v253, v253, v14
	v_fma_f32 v254, v13, v254, v103
	v_mul_f32_e32 v253, v253, v13
	v_fma_f32 v254, v12, v254, v102
	v_mul_f32_e32 v253, v253, v12
	v_fma_f32 v254, v11, v254, v101
	v_mul_f32_e32 v253, v253, v11
	v_fma_f32 v254, v10, v254, v100
	v_mul_f32_e32 v253, v253, v10
	v_fma_f32 v254, v9, v254, v99
	v_mul_f32_e32 v253, v253, v9
	v_fma_f32 v254, v8, v254, v98
	v_mul_f32_e32 v253, v253, v8
	v_fma_f32 v254, v7, v254, v97
	v_mul_f32_e32 v253, v253, v7
	v_fma_f32 v254, v6, v254, v96
	v_mul_f32_e32 v253, v253, v6
	v_fma_f32 v254, v5, v254, v95
	v_mul_f32_e32 v253, v253, v5
	v_fma_f32 v254, v4, v254, v94
	v_mul_f32_e32 v253, v253, v4
	v_fma_f32 v254, v3, v254, v93
	v_mul_f32_e32 v253, v253, v3
	v_fma_f32 v254, v2, v254, v92
	v_mul_f32_e32 v253, v253, v2
	v_fma_f32 v254, v1, v254, v91
	v_mul_f32_e32 v253, v253, v1
	v_fma_f32 v254, v0, v254, v90
	v_mul_f32_e32 v253, v253, v0
	v_mov_b32_e32 v138, v253
	v_mov_b32_e32 v139, v253
	s_nop 1
	v_permlane16_swap_b32_e32 v138, v139
	v_mov_b32_e32 v140, v138
	v_mov_b32_e32 v141, v139
	s_nop 1
	v_permlane32_swap_b32_e32 v138, v140
	v_permlane32_swap_b32_e32 v139, v141
	v_mov_b32_e32 v198, v254
	v_mov_b32_e32 v199, v254
	s_nop 1
	v_permlane16_swap_b32_e32 v198, v199
	v_mov_b32_e32 v200, v198
	v_mov_b32_e32 v201, v199
	s_nop 1
	v_permlane32_swap_b32_e32 v198, v200
	v_permlane32_swap_b32_e32 v199, v201
	v_mov_b32_e32 v202, 0
	v_fma_f32 v151, v141, v202, v201
	v_fma_f32 v150, v140, v151, v200
	v_fma_f32 v136, v139, v150, v199
	v_fma_f32 v254, v138, v136, v198
	v_mul_f32_e32 v253, v138, v139
	v_mul_f32_e32 v253, v253, v140
	v_mul_f32_e32 v200, v253, v141
	v_mov_b32_e32 v201, v254
	s_add_u32 s0, s71, 264
	s_lshl_b32 s0, s0, 12
	s_lshl_b32 s1, s56, 3
	s_add_u32 s0, s0, s1
	s_add_u32 s4, s18, s0
	s_addc_u32 s5, s19, 0
	global_store_dwordx2 v250, v[200:201], s[4:5]
	s_add_u32 s69, s69, 1
	s_cmp_lt_u32 s69, s70
	s_cbranch_scc1 .Lmy_lrua_tile
	s_waitcnt lgkmcnt(0)
	s_barrier

; __device__ __forceinline__ float bf2f(u16 h) { return __uint_as_float(((unsigned)h) << 16); }
; __device__ __forceinline__ void lru_tile(const Params& P, int chunk, int head, int pass, char* smem_raw) {
;     ...
;       f32x4 acc[8];
; #pragma unroll
;       for (int t = 0; t < 8; ++t) acc[t] = f32x4{0.f, 0.f, 0.f, 0.f};
; #pragma unroll
;       for (int s = 0; s < 2; ++s) {
;         const bf16x8 af = *reinterpret_cast<const bf16x8*>(&sm_uc[(sb * 64 + wid * 16 + (lane & 15)) * LDSS + s * 32 + (lane >> 4) * 8]);
; #pragma unroll
;         for (int t = 0; t < 8; ++t) {
;           const bf16x8 bfr = *reinterpret_cast<const bf16x8*>(&sm_w[(t * 16 + (lane & 15)) * LDSS + s * 32 + (lane >> 4) * 8]);
;           acc[t] = __builtin_amdgcn_mfma_f32_16x16x32_bf16(af, bfr, acc[t], 0, 0, 0);
;         }
;       }
; #pragma unroll
;       for (int tc = 0; tc < 4; ++tc)
; #pragma unroll
;         for (int reg = 0; reg < 4; ++reg) {
;           const int tl = wid * 16 + (lane >> 4) * 4 + reg;
;           const int c = 16 * tc + (lane & 15);
;           const float r = __builtin_amdgcn_rcpf(1.f + __builtin_amdgcn_exp2f(acc[tc][reg] + ba[tc]));
;           const float ii = __builtin_amdgcn_rcpf(1.f + __builtin_amdgcn_exp2f(acc[tc + 4][reg] + bi[tc]));
;           const float la = -c8[tc] * r;
;           const float a = __builtin_amdgcn_exp2f(la);
;           const float ucv = bf2f(sm_uc[(sb * 64 + tl) * LDSS + c]);
;           const float bt = __builtin_amdgcn_sqrtf(fmaxf(1.f - a * a, 0.f)) * (ii * ucv);
;           sm_a[tl * 64 + c] = a;
;           sm_b[tl * 64 + c] = bt;
;         }
.Lmy_lrub_nopf:
	ds_read_b128 v[76:79], v131 offset:0
	ds_read_b128 v[80:83], v133 offset:0
	ds_read_b128 v[122:125], v131 offset:512
	ds_read_b128 v[126:129], v133 offset:512
	s_waitcnt lgkmcnt(3)
	v_mfma_f32_16x16x32_bf16 v[0:3], v[76:79], v[238:241], 0
	v_mfma_f32_16x16x32_bf16 v[90:93], v[76:79], v[246:249], 0
	ds_read_b128 v[76:79], v131 offset:1024
	s_waitcnt lgkmcnt(3)
	v_mfma_f32_16x16x32_bf16 v[0:3], v[80:83], v[242:245], v[0:3]
	v_mfma_f32_16x16x32_bf16 v[90:93], v[80:83], v[194:197], v[90:93]
	ds_read_b128 v[80:83], v133 offset:1024
	s_waitcnt lgkmcnt(3)
	v_mfma_f32_16x16x32_bf16 v[4:7], v[122:125], v[238:241], 0
	v_mfma_f32_16x16x32_bf16 v[94:97], v[122:125], v[246:249], 0
	ds_read_b128 v[122:125], v131 offset:1536
	s_waitcnt lgkmcnt(3)
	v_mfma_f32_16x16x32_bf16 v[4:7], v[126:129], v[242:245], v[4:7]
	v_mfma_f32_16x16x32_bf16 v[94:97], v[126:129], v[194:197], v[94:97]
	ds_read_b128 v[126:129], v133 offset:1536
	s_waitcnt lgkmcnt(3)
	v_mfma_f32_16x16x32_bf16 v[8:11], v[76:79], v[238:241], 0
	v_mfma_f32_16x16x32_bf16 v[98:101], v[76:79], v[246:249], 0
	ds_read_b128 v[76:79], v131 offset:2048
	s_waitcnt lgkmcnt(3)
	v_mfma_f32_16x16x32_bf16 v[8:11], v[80:83], v[242:245], v[8:11]
	v_mfma_f32_16x16x32_bf16 v[98:101], v[80:83], v[194:197], v[98:101]
	ds_read_b128 v[80:83], v133 offset:2048
	s_waitcnt lgkmcnt(3)
	v_mfma_f32_16x16x32_bf16 v[12:15], v[122:125], v[238:241], 0
	v_mfma_f32_16x16x32_bf16 v[102:105], v[122:125], v[246:249], 0
	ds_read_b128 v[122:125], v131 offset:2560
	s_waitcnt lgkmcnt(3)
	v_mfma_f32_16x16x32_bf16 v[12:15], v[126:129], v[242:245], v[12:15]
	v_mfma_f32_16x16x32_bf16 v[102:105], v[126:129], v[194:197], v[102:105]
	ds_read_b128 v[126:129], v133 offset:2560
	s_waitcnt lgkmcnt(3)
	v_mfma_f32_16x16x32_bf16 v[16:19], v[76:79], v[238:241], 0
	v_mfma_f32_16x16x32_bf16 v[106:109], v[76:79], v[246:249], 0
	ds_read_b128 v[76:79], v131 offset:3072
	s_waitcnt lgkmcnt(3)
	v_mfma_f32_16x16x32_bf16 v[16:19], v[80:83], v[242:245], v[16:19]
	v_mfma_f32_16x16x32_bf16 v[106:109], v[80:83], v[194:197], v[106:109]
	ds_read_b128 v[80:83], v133 offset:3072
	s_waitcnt lgkmcnt(3)
	v_mfma_f32_16x16x32_bf16 v[20:23], v[122:125], v[238:241], 0
	v_mfma_f32_16x16x32_bf16 v[110:113], v[122:125], v[246:249], 0
	ds_read_b128 v[122:125], v131 offset:3584
	s_waitcnt lgkmcnt(3)
	v_mfma_f32_16x16x32_bf16 v[20:23], v[126:129], v[242:245], v[20:23]
	v_mfma_f32_16x16x32_bf16 v[110:113], v[126:129], v[194:197], v[110:113]
	ds_read_b128 v[126:129], v133 offset:3584
	s_waitcnt lgkmcnt(3)
	v_mfma_f32_16x16x32_bf16 v[24:27], v[76:79], v[238:241], 0
	v_mfma_f32_16x16x32_bf16 v[114:117], v[76:79], v[246:249], 0
	s_waitcnt lgkmcnt(2)
	v_mfma_f32_16x16x32_bf16 v[24:27], v[80:83], v[242:245], v[24:27]
	v_mfma_f32_16x16x32_bf16 v[114:117], v[80:83], v[194:197], v[114:117]
	s_waitcnt lgkmcnt(1)
	v_mfma_f32_16x16x32_bf16 v[28:31], v[122:125], v[238:241], 0
	v_mfma_f32_16x16x32_bf16 v[118:121], v[122:125], v[246:249], 0
	s_waitcnt lgkmcnt(0)
	v_mfma_f32_16x16x32_bf16 v[28:31], v[126:129], v[242:245], v[28:31]
	v_mfma_f32_16x16x32_bf16 v[118:121], v[126:129], v[194:197], v[118:121]
	s_lshl_b32 s0, s56, 8
	s_add_u32 s0, s0, 0x20000
	s_add_u32 s4, s20, s0
	s_addc_u32 s5, s21, 0
	global_load_dwordx4 v[238:241], v251, s[4:5]
	global_load_dwordx4 v[242:245], v251, s[4:5] offset:64
	s_add_u32 s4, s4, 0x2000
	s_addc_u32 s5, s5, 0
	global_load_dwordx4 v[246:249], v251, s[4:5]
	global_load_dwordx4 v[194:197], v251, s[4:5] offset:64
	s_nop 7
	s_nop 7
	v_add_f32_e32 v0, v0, v75
	v_add_f32_e32 v1, v1, v75
	v_add_f32_e32 v2, v2, v75
	v_add_f32_e32 v3, v3, v75
	v_add_f32_e32 v90, v90, v84
	v_add_f32_e32 v91, v91, v84
	v_add_f32_e32 v92, v92, v84
	v_add_f32_e32 v93, v93, v84
	v_exp_f32_e32 v0, v0
	v_exp_f32_e32 v1, v1
	v_exp_f32_e32 v2, v2
	v_exp_f32_e32 v3, v3
	v_exp_f32_e32 v90, v90
	v_exp_f32_e32 v91, v91
	v_exp_f32_e32 v92, v92
	v_exp_f32_e32 v93, v93
	v_add_f32_e32 v0, 1.0, v0
	v_add_f32_e32 v1, 1.0, v1
	v_add_f32_e32 v2, 1.0, v2
	v_add_f32_e32 v3, 1.0, v3
	v_add_f32_e32 v90, 1.0, v90
	v_add_f32_e32 v91, 1.0, v91
	v_add_f32_e32 v92, 1.0, v92
	v_add_f32_e32 v93, 1.0, v93
	v_rcp_f32_e32 v0, v0
	v_rcp_f32_e32 v1, v1
	v_rcp_f32_e32 v2, v2
	v_rcp_f32_e32 v3, v3
	v_rcp_f32_e32 v90, v90
	v_rcp_f32_e32 v91, v91
	v_rcp_f32_e32 v92, v92
	v_rcp_f32_e32 v93, v93
	v_mul_f32_e32 v0, v85, v0
	v_mul_f32_e32 v1, v85, v1
	v_mul_f32_e32 v2, v85, v2
	v_mul_f32_e32 v3, v85, v3
	v_mul_f32_e32 v90, v90, v162
	v_mul_f32_e32 v91, v91, v163
	v_mul_f32_e32 v92, v92, v164
	v_mul_f32_e32 v93, v93, v165
	v_exp_f32_e32 v0, v0
	v_exp_f32_e32 v1, v1
	v_exp_f32_e32 v2, v2
	v_exp_f32_e32 v3, v3
	s_nop 0
	v_fma_f32 v138, -v0, v0, 1.0 clamp
	v_fma_f32 v139, -v1, v1, 1.0 clamp
	v_fma_f32 v140, -v2, v2, 1.0 clamp
	v_fma_f32 v141, -v3, v3, 1.0 clamp
	v_sqrt_f32_e32 v138, v138
	v_sqrt_f32_e32 v139, v139
	v_sqrt_f32_e32 v140, v140
	v_sqrt_f32_e32 v141, v141
	s_nop 0
	v_mul_f32_e32 v90, v138, v90
	v_mul_f32_e32 v91, v139, v91
	v_mul_f32_e32 v92, v140, v92
	v_mul_f32_e32 v93, v141, v93
	v_add_f32_e32 v4, v4, v75
	v_add_f32_e32 v5, v5, v75
	v_add_f32_e32 v6, v6, v75
	v_add_f32_e32 v7, v7, v75
	v_add_f32_e32 v94, v94, v84
	v_add_f32_e32 v95, v95, v84
	v_add_f32_e32 v96, v96, v84
	v_add_f32_e32 v97, v97, v84
	v_exp_f32_e32 v4, v4
	v_exp_f32_e32 v5, v5
	v_exp_f32_e32 v6, v6
	v_exp_f32_e32 v7, v7
	v_exp_f32_e32 v94, v94
	v_exp_f32_e32 v95, v95
	v_exp_f32_e32 v96, v96
	v_exp_f32_e32 v97, v97
	v_add_f32_e32 v4, 1.0, v4
	v_add_f32_e32 v5, 1.0, v5
	v_add_f32_e32 v6, 1.0, v6
	v_add_f32_e32 v7, 1.0, v7
	v_add_f32_e32 v94, 1.0, v94
	v_add_f32_e32 v95, 1.0, v95
	v_add_f32_e32 v96, 1.0, v96
	v_add_f32_e32 v97, 1.0, v97
; __device__ __forceinline__ float bf2f(u16 h) { return __uint_as_float(((unsigned)h) << 16); }
; __device__ __forceinline__ void lru_tile(const Params& P, int chunk, int head, int pass, char* smem_raw) {
;     ...
;       for (int tc = 0; tc < 4; ++tc)
; #pragma unroll
;         for (int reg = 0; reg < 4; ++reg) {
;           const int tl = wid * 16 + (lane >> 4) * 4 + reg;
;           const int c = 16 * tc + (lane & 15);
;           const float r = __builtin_amdgcn_rcpf(1.f + __builtin_amdgcn_exp2f(acc[tc][reg] + ba[tc]));
;           const float ii = __builtin_amdgcn_rcpf(1.f + __builtin_amdgcn_exp2f(acc[tc + 4][reg] + bi[tc]));
;           const float la = -c8[tc] * r;
;           const float a = __builtin_amdgcn_exp2f(la);
;           const float ucv = bf2f(sm_uc[(sb * 64 + tl) * LDSS + c]);
;           const float bt = __builtin_amdgcn_sqrtf(fmaxf(1.f - a * a, 0.f)) * (ii * ucv);
;           sm_a[tl * 64 + c] = a;
;           sm_b[tl * 64 + c] = bt;
;         }
	v_rcp_f32_e32 v4, v4
	v_rcp_f32_e32 v5, v5
	v_rcp_f32_e32 v6, v6
	v_rcp_f32_e32 v7, v7
	v_rcp_f32_e32 v94, v94
	v_rcp_f32_e32 v95, v95
	v_rcp_f32_e32 v96, v96
	v_rcp_f32_e32 v97, v97
	v_mul_f32_e32 v4, v85, v4
	v_mul_f32_e32 v5, v85, v5
	v_mul_f32_e32 v6, v85, v6
	v_mul_f32_e32 v7, v85, v7
	v_mul_f32_e32 v94, v94, v166
	v_mul_f32_e32 v95, v95, v167
	v_mul_f32_e32 v96, v96, v168
	v_mul_f32_e32 v97, v97, v169
	v_exp_f32_e32 v4, v4
	v_exp_f32_e32 v5, v5
	v_exp_f32_e32 v6, v6
	v_exp_f32_e32 v7, v7
	s_nop 0
	v_fma_f32 v138, -v4, v4, 1.0 clamp
	v_fma_f32 v139, -v5, v5, 1.0 clamp
	v_fma_f32 v140, -v6, v6, 1.0 clamp
	v_fma_f32 v141, -v7, v7, 1.0 clamp
	v_sqrt_f32_e32 v138, v138
	v_sqrt_f32_e32 v139, v139
	v_sqrt_f32_e32 v140, v140
	v_sqrt_f32_e32 v141, v141
	s_nop 0
	v_mul_f32_e32 v94, v138, v94
	v_mul_f32_e32 v95, v139, v95
	v_mul_f32_e32 v96, v140, v96
	v_mul_f32_e32 v97, v141, v97
	v_add_f32_e32 v8, v8, v75
	v_add_f32_e32 v9, v9, v75
	v_add_f32_e32 v10, v10, v75
	v_add_f32_e32 v11, v11, v75
	v_add_f32_e32 v98, v98, v84
	v_add_f32_e32 v99, v99, v84
	v_add_f32_e32 v100, v100, v84
	v_add_f32_e32 v101, v101, v84
	v_exp_f32_e32 v8, v8
	v_exp_f32_e32 v9, v9
	v_exp_f32_e32 v10, v10
	v_exp_f32_e32 v11, v11
	v_exp_f32_e32 v98, v98
	v_exp_f32_e32 v99, v99
	v_exp_f32_e32 v100, v100
	v_exp_f32_e32 v101, v101
	v_add_f32_e32 v8, 1.0, v8
	v_add_f32_e32 v9, 1.0, v9
	v_add_f32_e32 v10, 1.0, v10
	v_add_f32_e32 v11, 1.0, v11
	v_add_f32_e32 v98, 1.0, v98
	v_add_f32_e32 v99, 1.0, v99
	v_add_f32_e32 v100, 1.0, v100
	v_add_f32_e32 v101, 1.0, v101
	v_rcp_f32_e32 v8, v8
	v_rcp_f32_e32 v9, v9
	v_rcp_f32_e32 v10, v10
	v_rcp_f32_e32 v11, v11
	v_rcp_f32_e32 v98, v98
	v_rcp_f32_e32 v99, v99
	v_rcp_f32_e32 v100, v100
	v_rcp_f32_e32 v101, v101
	v_mul_f32_e32 v8, v85, v8
	v_mul_f32_e32 v9, v85, v9
	v_mul_f32_e32 v10, v85, v10
	v_mul_f32_e32 v11, v85, v11
	v_mul_f32_e32 v98, v98, v170
	v_mul_f32_e32 v99, v99, v171
	v_mul_f32_e32 v100, v100, v172
	v_mul_f32_e32 v101, v101, v173
	v_exp_f32_e32 v8, v8
	v_exp_f32_e32 v9, v9
	v_exp_f32_e32 v10, v10
	v_exp_f32_e32 v11, v11
	s_nop 0
	v_fma_f32 v138, -v8, v8, 1.0 clamp
	v_fma_f32 v139, -v9, v9, 1.0 clamp
	v_fma_f32 v140, -v10, v10, 1.0 clamp
	v_fma_f32 v141, -v11, v11, 1.0 clamp
	v_sqrt_f32_e32 v138, v138
	v_sqrt_f32_e32 v139, v139
	v_sqrt_f32_e32 v140, v140
	v_sqrt_f32_e32 v141, v141
	s_nop 0
	v_mul_f32_e32 v98, v138, v98
	v_mul_f32_e32 v99, v139, v99
	v_mul_f32_e32 v100, v140, v100
	v_mul_f32_e32 v101, v141, v101
	v_add_f32_e32 v12, v12, v75
	v_add_f32_e32 v13, v13, v75
	v_add_f32_e32 v14, v14, v75
	v_add_f32_e32 v15, v15, v75
	v_add_f32_e32 v102, v102, v84
	v_add_f32_e32 v103, v103, v84
	v_add_f32_e32 v104, v104, v84
	v_add_f32_e32 v105, v105, v84
	v_exp_f32_e32 v12, v12
	v_exp_f32_e32 v13, v13
	v_exp_f32_e32 v14, v14
	v_exp_f32_e32 v15, v15
	v_exp_f32_e32 v102, v102
	v_exp_f32_e32 v103, v103
	v_exp_f32_e32 v104, v104
	v_exp_f32_e32 v105, v105
	v_add_f32_e32 v12, 1.0, v12
	v_add_f32_e32 v13, 1.0, v13
	v_add_f32_e32 v14, 1.0, v14
	v_add_f32_e32 v15, 1.0, v15
	v_add_f32_e32 v102, 1.0, v102
	v_add_f32_e32 v103, 1.0, v103
	v_add_f32_e32 v104, 1.0, v104
	v_add_f32_e32 v105, 1.0, v105
	v_rcp_f32_e32 v12, v12
	v_rcp_f32_e32 v13, v13
	v_rcp_f32_e32 v14, v14
	v_rcp_f32_e32 v15, v15
	v_rcp_f32_e32 v102, v102
	v_rcp_f32_e32 v103, v103
	v_rcp_f32_e32 v104, v104
	v_rcp_f32_e32 v105, v105
	v_mul_f32_e32 v12, v85, v12
	v_mul_f32_e32 v13, v85, v13
	v_mul_f32_e32 v14, v85, v14
	v_mul_f32_e32 v15, v85, v15
	v_mul_f32_e32 v102, v102, v174
	v_mul_f32_e32 v103, v103, v175
	v_mul_f32_e32 v104, v104, v176
	v_mul_f32_e32 v105, v105, v177
	v_exp_f32_e32 v12, v12
	v_exp_f32_e32 v13, v13
	v_exp_f32_e32 v14, v14
	v_exp_f32_e32 v15, v15
	s_nop 0
	v_fma_f32 v138, -v12, v12, 1.0 clamp
	v_fma_f32 v139, -v13, v13, 1.0 clamp
	v_fma_f32 v140, -v14, v14, 1.0 clamp
	v_fma_f32 v141, -v15, v15, 1.0 clamp
	v_sqrt_f32_e32 v138, v138
	v_sqrt_f32_e32 v139, v139
	v_sqrt_f32_e32 v140, v140
	v_sqrt_f32_e32 v141, v141
	s_nop 0
	v_mul_f32_e32 v102, v138, v102
	v_mul_f32_e32 v103, v139, v103
	v_mul_f32_e32 v104, v140, v104
	v_mul_f32_e32 v105, v141, v105
	v_add_f32_e32 v16, v16, v75
	v_add_f32_e32 v17, v17, v75
	v_add_f32_e32 v18, v18, v75
	v_add_f32_e32 v19, v19, v75
	v_add_f32_e32 v106, v106, v84
	v_add_f32_e32 v107, v107, v84
	v_add_f32_e32 v108, v108, v84
	v_add_f32_e32 v109, v109, v84
	v_exp_f32_e32 v16, v16
	v_exp_f32_e32 v17, v17
	v_exp_f32_e32 v18, v18
	v_exp_f32_e32 v19, v19
	v_exp_f32_e32 v106, v106
	v_exp_f32_e32 v107, v107
	v_exp_f32_e32 v108, v108
	v_exp_f32_e32 v109, v109
	v_add_f32_e32 v16, 1.0, v16
	v_add_f32_e32 v17, 1.0, v17
	v_add_f32_e32 v18, 1.0, v18
	v_add_f32_e32 v19, 1.0, v19
	v_add_f32_e32 v106, 1.0, v106
	v_add_f32_e32 v107, 1.0, v107
	v_add_f32_e32 v108, 1.0, v108
	v_add_f32_e32 v109, 1.0, v109
	v_rcp_f32_e32 v16, v16
	v_rcp_f32_e32 v17, v17
	v_rcp_f32_e32 v18, v18
	v_rcp_f32_e32 v19, v19
	v_rcp_f32_e32 v106, v106
	v_rcp_f32_e32 v107, v107
	v_rcp_f32_e32 v108, v108
	v_rcp_f32_e32 v109, v109
	v_mul_f32_e32 v16, v85, v16
	v_mul_f32_e32 v17, v85, v17
	v_mul_f32_e32 v18, v85, v18
	v_mul_f32_e32 v19, v85, v19
	v_mul_f32_e32 v106, v106, v178
	v_mul_f32_e32 v107, v107, v179
	v_mul_f32_e32 v108, v108, v180
	v_mul_f32_e32 v109, v109, v181
	v_exp_f32_e32 v16, v16
	v_exp_f32_e32 v17, v17
	v_exp_f32_e32 v18, v18
	v_exp_f32_e32 v19, v19
	s_nop 0
	v_fma_f32 v138, -v16, v16, 1.0 clamp
	v_fma_f32 v139, -v17, v17, 1.0 clamp
	v_fma_f32 v140, -v18, v18, 1.0 clamp
	v_fma_f32 v141, -v19, v19, 1.0 clamp
	v_sqrt_f32_e32 v138, v138
	v_sqrt_f32_e32 v139, v139
	v_sqrt_f32_e32 v140, v140
	v_sqrt_f32_e32 v141, v141
	s_nop 0
	v_mul_f32_e32 v106, v138, v106
	v_mul_f32_e32 v107, v139, v107
; __device__ __forceinline__ float bf2f(u16 h) { return __uint_as_float(((unsigned)h) << 16); }
; __device__ __forceinline__ void lru_tile(const Params& P, int chunk, int head, int pass, char* smem_raw) {
;     ...
;       for (int tc = 0; tc < 4; ++tc)
; #pragma unroll
;         for (int reg = 0; reg < 4; ++reg) {
;           const int tl = wid * 16 + (lane >> 4) * 4 + reg;
;           const int c = 16 * tc + (lane & 15);
;           const float r = __builtin_amdgcn_rcpf(1.f + __builtin_amdgcn_exp2f(acc[tc][reg] + ba[tc]));
;           const float ii = __builtin_amdgcn_rcpf(1.f + __builtin_amdgcn_exp2f(acc[tc + 4][reg] + bi[tc]));
;           const float la = -c8[tc] * r;
;           const float a = __builtin_amdgcn_exp2f(la);
;           const float ucv = bf2f(sm_uc[(sb * 64 + tl) * LDSS + c]);
;           const float bt = __builtin_amdgcn_sqrtf(fmaxf(1.f - a * a, 0.f)) * (ii * ucv);
;           sm_a[tl * 64 + c] = a;
;           sm_b[tl * 64 + c] = bt;
;         }
;       __syncthreads();
;       const int pos = (d == 0) ? q : 3 - q;
;       {
;         float Pp = 1.f, H = 0.f;
; #pragma unroll 4
;         for (int i = 0; i < 16; ++i) {
;           const int tl = (d == 0) ? (q * 16 + i) : (q * 16 + 15 - i);
;           const float a = sm_a[tl * 64 + ch], b = sm_b[tl * 64 + ch];
;           H = a * H + b; Pp *= a;
;         }
;         sm_ph[pos * 64 + ch] = make_float2(Pp, H);
	v_mul_f32_e32 v108, v140, v108
	v_mul_f32_e32 v109, v141, v109
	v_add_f32_e32 v20, v20, v75
	v_add_f32_e32 v21, v21, v75
	v_add_f32_e32 v22, v22, v75
	v_add_f32_e32 v23, v23, v75
	v_add_f32_e32 v110, v110, v84
	v_add_f32_e32 v111, v111, v84
	v_add_f32_e32 v112, v112, v84
	v_add_f32_e32 v113, v113, v84
	v_exp_f32_e32 v20, v20
	v_exp_f32_e32 v21, v21
	v_exp_f32_e32 v22, v22
	v_exp_f32_e32 v23, v23
	v_exp_f32_e32 v110, v110
	v_exp_f32_e32 v111, v111
	v_exp_f32_e32 v112, v112
	v_exp_f32_e32 v113, v113
	v_add_f32_e32 v20, 1.0, v20
	v_add_f32_e32 v21, 1.0, v21
	v_add_f32_e32 v22, 1.0, v22
	v_add_f32_e32 v23, 1.0, v23
	v_add_f32_e32 v110, 1.0, v110
	v_add_f32_e32 v111, 1.0, v111
	v_add_f32_e32 v112, 1.0, v112
	v_add_f32_e32 v113, 1.0, v113
	v_rcp_f32_e32 v20, v20
	v_rcp_f32_e32 v21, v21
	v_rcp_f32_e32 v22, v22
	v_rcp_f32_e32 v23, v23
	v_rcp_f32_e32 v110, v110
	v_rcp_f32_e32 v111, v111
	v_rcp_f32_e32 v112, v112
	v_rcp_f32_e32 v113, v113
	v_mul_f32_e32 v20, v85, v20
	v_mul_f32_e32 v21, v85, v21
	v_mul_f32_e32 v22, v85, v22
	v_mul_f32_e32 v23, v85, v23
	v_mul_f32_e32 v110, v110, v182
	v_mul_f32_e32 v111, v111, v183
	v_mul_f32_e32 v112, v112, v184
	v_mul_f32_e32 v113, v113, v185
	v_exp_f32_e32 v20, v20
	v_exp_f32_e32 v21, v21
	v_exp_f32_e32 v22, v22
	v_exp_f32_e32 v23, v23
	s_nop 0
	v_fma_f32 v138, -v20, v20, 1.0 clamp
	v_fma_f32 v139, -v21, v21, 1.0 clamp
	v_fma_f32 v140, -v22, v22, 1.0 clamp
	v_fma_f32 v141, -v23, v23, 1.0 clamp
	v_sqrt_f32_e32 v138, v138
	v_sqrt_f32_e32 v139, v139
	v_sqrt_f32_e32 v140, v140
	v_sqrt_f32_e32 v141, v141
	s_nop 0
	v_mul_f32_e32 v110, v138, v110
	v_mul_f32_e32 v111, v139, v111
	v_mul_f32_e32 v112, v140, v112
	v_mul_f32_e32 v113, v141, v113
	v_add_f32_e32 v24, v24, v75
	v_add_f32_e32 v25, v25, v75
	v_add_f32_e32 v26, v26, v75
	v_add_f32_e32 v27, v27, v75
	v_add_f32_e32 v114, v114, v84
	v_add_f32_e32 v115, v115, v84
	v_add_f32_e32 v116, v116, v84
	v_add_f32_e32 v117, v117, v84
	v_exp_f32_e32 v24, v24
	v_exp_f32_e32 v25, v25
	v_exp_f32_e32 v26, v26
	v_exp_f32_e32 v27, v27
	v_exp_f32_e32 v114, v114
	v_exp_f32_e32 v115, v115
	v_exp_f32_e32 v116, v116
	v_exp_f32_e32 v117, v117
	v_add_f32_e32 v24, 1.0, v24
	v_add_f32_e32 v25, 1.0, v25
	v_add_f32_e32 v26, 1.0, v26
	v_add_f32_e32 v27, 1.0, v27
	v_add_f32_e32 v114, 1.0, v114
	v_add_f32_e32 v115, 1.0, v115
	v_add_f32_e32 v116, 1.0, v116
	v_add_f32_e32 v117, 1.0, v117
	v_rcp_f32_e32 v24, v24
	v_rcp_f32_e32 v25, v25
	v_rcp_f32_e32 v26, v26
	v_rcp_f32_e32 v27, v27
	v_rcp_f32_e32 v114, v114
	v_rcp_f32_e32 v115, v115
	v_rcp_f32_e32 v116, v116
	v_rcp_f32_e32 v117, v117
	v_mul_f32_e32 v24, v85, v24
	v_mul_f32_e32 v25, v85, v25
	v_mul_f32_e32 v26, v85, v26
	v_mul_f32_e32 v27, v85, v27
	v_mul_f32_e32 v114, v114, v186
	v_mul_f32_e32 v115, v115, v187
	v_mul_f32_e32 v116, v116, v188
	v_mul_f32_e32 v117, v117, v189
	v_exp_f32_e32 v24, v24
	v_exp_f32_e32 v25, v25
	v_exp_f32_e32 v26, v26
	v_exp_f32_e32 v27, v27
	s_nop 0
	v_fma_f32 v138, -v24, v24, 1.0 clamp
	v_fma_f32 v139, -v25, v25, 1.0 clamp
	v_fma_f32 v140, -v26, v26, 1.0 clamp
	v_fma_f32 v141, -v27, v27, 1.0 clamp
	v_sqrt_f32_e32 v138, v138
	v_sqrt_f32_e32 v139, v139
	v_sqrt_f32_e32 v140, v140
	v_sqrt_f32_e32 v141, v141
	s_nop 0
	v_mul_f32_e32 v114, v138, v114
	v_mul_f32_e32 v115, v139, v115
	v_mul_f32_e32 v116, v140, v116
	v_mul_f32_e32 v117, v141, v117
	v_add_f32_e32 v28, v28, v75
	v_add_f32_e32 v29, v29, v75
	v_add_f32_e32 v30, v30, v75
	v_add_f32_e32 v31, v31, v75
	v_add_f32_e32 v118, v118, v84
	v_add_f32_e32 v119, v119, v84
	v_add_f32_e32 v120, v120, v84
	v_add_f32_e32 v121, v121, v84
	v_exp_f32_e32 v28, v28
	v_exp_f32_e32 v29, v29
	v_exp_f32_e32 v30, v30
	v_exp_f32_e32 v31, v31
	v_exp_f32_e32 v118, v118
	v_exp_f32_e32 v119, v119
	v_exp_f32_e32 v120, v120
	v_exp_f32_e32 v121, v121
	v_add_f32_e32 v28, 1.0, v28
	v_add_f32_e32 v29, 1.0, v29
	v_add_f32_e32 v30, 1.0, v30
	v_add_f32_e32 v31, 1.0, v31
	v_add_f32_e32 v118, 1.0, v118
	v_add_f32_e32 v119, 1.0, v119
	v_add_f32_e32 v120, 1.0, v120
	v_add_f32_e32 v121, 1.0, v121
	v_rcp_f32_e32 v28, v28
	v_rcp_f32_e32 v29, v29
	v_rcp_f32_e32 v30, v30
	v_rcp_f32_e32 v31, v31
	v_rcp_f32_e32 v118, v118
	v_rcp_f32_e32 v119, v119
	v_rcp_f32_e32 v120, v120
	v_rcp_f32_e32 v121, v121
	v_mul_f32_e32 v28, v85, v28
	v_mul_f32_e32 v29, v85, v29
	v_mul_f32_e32 v30, v85, v30
	v_mul_f32_e32 v31, v85, v31
	v_mul_f32_e32 v118, v118, v190
	v_mul_f32_e32 v119, v119, v191
	v_mul_f32_e32 v120, v120, v192
	v_mul_f32_e32 v121, v121, v193
	v_exp_f32_e32 v28, v28
	v_exp_f32_e32 v29, v29
	v_exp_f32_e32 v30, v30
	v_exp_f32_e32 v31, v31
	s_nop 0
	v_fma_f32 v138, -v28, v28, 1.0 clamp
	v_fma_f32 v139, -v29, v29, 1.0 clamp
	v_fma_f32 v140, -v30, v30, 1.0 clamp
	v_fma_f32 v141, -v31, v31, 1.0 clamp
	v_sqrt_f32_e32 v138, v138
	v_sqrt_f32_e32 v139, v139
	v_sqrt_f32_e32 v140, v140
	v_sqrt_f32_e32 v141, v141
	s_nop 0
	v_mul_f32_e32 v118, v138, v118
	v_mul_f32_e32 v119, v139, v119
	v_mul_f32_e32 v120, v140, v120
	v_mul_f32_e32 v121, v141, v121
	v_mov_b32_e32 v253, v0
	v_mov_b32_e32 v254, v90
	v_fma_f32 v254, v1, v254, v91
	v_mul_f32_e32 v253, v253, v1
	v_fma_f32 v254, v2, v254, v92
	v_mul_f32_e32 v253, v253, v2
	v_fma_f32 v254, v3, v254, v93
	v_mul_f32_e32 v253, v253, v3
	v_fma_f32 v254, v4, v254, v94
	v_mul_f32_e32 v253, v253, v4
	v_fma_f32 v254, v5, v254, v95
	v_mul_f32_e32 v253, v253, v5
	v_fma_f32 v254, v6, v254, v96
	v_mul_f32_e32 v253, v253, v6
	v_fma_f32 v254, v7, v254, v97
	v_mul_f32_e32 v253, v253, v7
	v_fma_f32 v254, v8, v254, v98
	v_mul_f32_e32 v253, v253, v8
	v_fma_f32 v254, v9, v254, v99
	v_mul_f32_e32 v253, v253, v9
	v_fma_f32 v254, v10, v254, v100
	v_mul_f32_e32 v253, v253, v10
	v_fma_f32 v254, v11, v254, v101
; __device__ __forceinline__ float bf2f(u16 h) { return __uint_as_float(((unsigned)h) << 16); }
; __device__ __forceinline__ void lru_tile(const Params& P, int chunk, int head, int pass, char* smem_raw) {
;     ...
;       {
;         float Pp = 1.f, H = 0.f;
; #pragma unroll 4
;         for (int i = 0; i < 16; ++i) {
;           const int tl = (d == 0) ? (q * 16 + i) : (q * 16 + 15 - i);
;           const float a = sm_a[tl * 64 + ch], b = sm_b[tl * 64 + ch];
;           H = a * H + b; Pp *= a;
;         }
;         sm_ph[pos * 64 + ch] = make_float2(Pp, H);
;       }
;       __syncthreads();
;       const float2 p0 = sm_ph[ch], p1 = sm_ph[64 + ch], p2 = sm_ph[128 + ch], p3 = sm_ph[192 + ch];
;       if (pass == 2) {
;         float hin = cB;
;         if (pos > 0) hin = p0.x * hin + p0.y;
;         if (pos > 1) hin = p1.x * hin + p1.y;
;         if (pos > 2) hin = p2.x * hin + p2.y;
;         float h = hin;
;         float hfp[16], gp[16];
;         if (d == 1) {
; #pragma unroll
;           for (int i = 0; i < 16; ++i) {
;             const long rowp = row0 + sb * 64 + q * 16 + 15 - i;
;             hfp[i] = hfbuf[rowp * 512 + gch];
;             gp[i] = bf2f(P.zq[rowp * 1536 + 512 + gch]);
;           }
;         }
; #pragma unroll
;         for (int i = 0; i < 16; ++i) {
;           const int tl = (d == 0) ? (q * 16 + i) : (q * 16 + 15 - i);
;           const float a = sm_a[tl * 64 + ch], b = sm_b[tl * 64 + ch];
;           h = a * h + b;
;           const long row = row0 + sb * 64 + tl;
;           if (d == 0) {
;             hfw[row * 512 + gch] = h;
	v_mul_f32_e32 v253, v253, v11
	v_fma_f32 v254, v12, v254, v102
	v_mul_f32_e32 v253, v253, v12
	v_fma_f32 v254, v13, v254, v103
	v_mul_f32_e32 v253, v253, v13
	v_fma_f32 v254, v14, v254, v104
	v_mul_f32_e32 v253, v253, v14
	v_fma_f32 v254, v15, v254, v105
	v_mul_f32_e32 v253, v253, v15
	v_fma_f32 v254, v16, v254, v106
	v_mul_f32_e32 v253, v253, v16
	v_fma_f32 v254, v17, v254, v107
	v_mul_f32_e32 v253, v253, v17
	v_fma_f32 v254, v18, v254, v108
	v_mul_f32_e32 v253, v253, v18
	v_fma_f32 v254, v19, v254, v109
	v_mul_f32_e32 v253, v253, v19
	v_fma_f32 v254, v20, v254, v110
	v_mul_f32_e32 v253, v253, v20
	v_fma_f32 v254, v21, v254, v111
	v_mul_f32_e32 v253, v253, v21
	v_fma_f32 v254, v22, v254, v112
	v_mul_f32_e32 v253, v253, v22
	v_fma_f32 v254, v23, v254, v113
	v_mul_f32_e32 v253, v253, v23
	v_fma_f32 v254, v24, v254, v114
	v_mul_f32_e32 v253, v253, v24
	v_fma_f32 v254, v25, v254, v115
	v_mul_f32_e32 v253, v253, v25
	v_fma_f32 v254, v26, v254, v116
	v_mul_f32_e32 v253, v253, v26
	v_fma_f32 v254, v27, v254, v117
	v_mul_f32_e32 v253, v253, v27
	v_fma_f32 v254, v28, v254, v118
	v_mul_f32_e32 v253, v253, v28
	v_fma_f32 v254, v29, v254, v119
	v_mul_f32_e32 v253, v253, v29
	v_fma_f32 v254, v30, v254, v120
	v_mul_f32_e32 v253, v253, v30
	v_fma_f32 v254, v31, v254, v121
	v_mul_f32_e32 v253, v253, v31
	v_mov_b32_e32 v138, v253
	v_mov_b32_e32 v139, v253
	s_nop 1
	v_permlane16_swap_b32_e32 v138, v139
	v_mov_b32_e32 v140, v138
	v_mov_b32_e32 v141, v139
	s_nop 1
	v_permlane32_swap_b32_e32 v138, v140
	v_permlane32_swap_b32_e32 v139, v141
	v_mov_b32_e32 v198, v254
	v_mov_b32_e32 v199, v254
	s_nop 1
	v_permlane16_swap_b32_e32 v198, v199
	v_mov_b32_e32 v200, v198
	v_mov_b32_e32 v201, v199
	s_nop 1
	v_permlane32_swap_b32_e32 v198, v200
	v_permlane32_swap_b32_e32 v199, v201
	v_mov_b32_e32 v136, v148
	v_fma_f32 v150, v138, v136, v198
	v_fma_f32 v151, v139, v150, v199
	v_fma_f32 v202, v140, v151, v200
	v_mov_b32_e32 v254, v136
	v_cndmask_b32_e64 v254, v254, v150, s[72:73]
	v_cndmask_b32_e64 v254, v254, v151, s[74:75]
	v_cndmask_b32_e64 v254, v254, v202, s[76:77]
	v_fma_f32 v205, v0, v254, v90
	v_fma_f32 v206, v1, v205, v91
	v_fma_f32 v207, v2, v206, v92
	v_fma_f32 v208, v3, v207, v93
	v_fma_f32 v209, v4, v208, v94
	v_fma_f32 v210, v5, v209, v95
	v_fma_f32 v211, v6, v210, v96
	v_fma_f32 v212, v7, v211, v97
	v_fma_f32 v213, v8, v212, v98
	v_fma_f32 v214, v9, v213, v99
	v_fma_f32 v215, v10, v214, v100
	v_fma_f32 v216, v11, v215, v101
	v_fma_f32 v217, v12, v216, v102
	v_fma_f32 v218, v13, v217, v103
	v_fma_f32 v219, v14, v218, v104
	v_fma_f32 v220, v15, v219, v105
	v_fma_f32 v221, v16, v220, v106
	v_fma_f32 v222, v17, v221, v107
	v_fma_f32 v223, v18, v222, v108
	v_fma_f32 v224, v19, v223, v109
	v_fma_f32 v225, v20, v224, v110
	v_fma_f32 v226, v21, v225, v111
	v_fma_f32 v227, v22, v226, v112
	v_fma_f32 v228, v23, v227, v113
	v_fma_f32 v229, v24, v228, v114
	v_fma_f32 v230, v25, v229, v115
	v_fma_f32 v231, v26, v230, v116
	v_fma_f32 v232, v27, v231, v117
	v_fma_f32 v233, v28, v232, v118
	v_fma_f32 v234, v29, v233, v119
	v_fma_f32 v235, v30, v234, v120
	v_fma_f32 v236, v31, v235, v121
	ds_read_b128 v[76:79], v131 offset:0
	ds_read_b128 v[80:83], v133 offset:0
	ds_read_b128 v[122:125], v131 offset:512
	ds_read_b128 v[126:129], v133 offset:512
	s_waitcnt vmcnt(0)
	s_waitcnt lgkmcnt(3)
	v_mfma_f32_16x16x32_bf16 v[0:3], v[76:79], v[238:241], 0
	v_mfma_f32_16x16x32_bf16 v[90:93], v[76:79], v[246:249], 0
	ds_read_b128 v[76:79], v131 offset:1024
	s_waitcnt lgkmcnt(3)
	v_mfma_f32_16x16x32_bf16 v[0:3], v[80:83], v[242:245], v[0:3]
	v_mfma_f32_16x16x32_bf16 v[90:93], v[80:83], v[194:197], v[90:93]
	ds_read_b128 v[80:83], v133 offset:1024
	s_waitcnt lgkmcnt(3)
	v_mfma_f32_16x16x32_bf16 v[4:7], v[122:125], v[238:241], 0
	v_mfma_f32_16x16x32_bf16 v[94:97], v[122:125], v[246:249], 0
	ds_read_b128 v[122:125], v131 offset:1536
	s_waitcnt lgkmcnt(3)
	v_mfma_f32_16x16x32_bf16 v[4:7], v[126:129], v[242:245], v[4:7]
	v_mfma_f32_16x16x32_bf16 v[94:97], v[126:129], v[194:197], v[94:97]
	ds_read_b128 v[126:129], v133 offset:1536
	s_waitcnt lgkmcnt(3)
	v_mfma_f32_16x16x32_bf16 v[8:11], v[76:79], v[238:241], 0
	v_mfma_f32_16x16x32_bf16 v[98:101], v[76:79], v[246:249], 0
	ds_read_b128 v[76:79], v131 offset:2048
	s_waitcnt lgkmcnt(3)
	v_mfma_f32_16x16x32_bf16 v[8:11], v[80:83], v[242:245], v[8:11]
	v_mfma_f32_16x16x32_bf16 v[98:101], v[80:83], v[194:197], v[98:101]
	ds_read_b128 v[80:83], v133 offset:2048
	s_waitcnt lgkmcnt(3)
	v_mfma_f32_16x16x32_bf16 v[12:15], v[122:125], v[238:241], 0
	v_mfma_f32_16x16x32_bf16 v[102:105], v[122:125], v[246:249], 0
	ds_read_b128 v[122:125], v131 offset:2560
	s_waitcnt lgkmcnt(3)
	v_mfma_f32_16x16x32_bf16 v[12:15], v[126:129], v[242:245], v[12:15]
	v_mfma_f32_16x16x32_bf16 v[102:105], v[126:129], v[194:197], v[102:105]
	ds_read_b128 v[126:129], v133 offset:2560
	s_waitcnt lgkmcnt(3)
	v_mfma_f32_16x16x32_bf16 v[16:19], v[76:79], v[238:241], 0
	v_mfma_f32_16x16x32_bf16 v[106:109], v[76:79], v[246:249], 0
	ds_read_b128 v[76:79], v131 offset:3072
	s_waitcnt lgkmcnt(3)
	v_mfma_f32_16x16x32_bf16 v[16:19], v[80:83], v[242:245], v[16:19]
	v_mfma_f32_16x16x32_bf16 v[106:109], v[80:83], v[194:197], v[106:109]
	ds_read_b128 v[80:83], v133 offset:3072
	s_waitcnt lgkmcnt(3)
	v_mfma_f32_16x16x32_bf16 v[20:23], v[122:125], v[238:241], 0
	v_mfma_f32_16x16x32_bf16 v[110:113], v[122:125], v[246:249], 0
	ds_read_b128 v[122:125], v131 offset:3584
	s_waitcnt lgkmcnt(3)
	v_mfma_f32_16x16x32_bf16 v[20:23], v[126:129], v[242:245], v[20:23]
	v_mfma_f32_16x16x32_bf16 v[110:113], v[126:129], v[194:197], v[110:113]
	ds_read_b128 v[126:129], v133 offset:3584
	s_waitcnt lgkmcnt(3)
; __device__ __forceinline__ float bf2f(u16 h) { return __uint_as_float(((unsigned)h) << 16); }
; __device__ __forceinline__ void lru_tile(const Params& P, int chunk, int head, int pass, char* smem_raw) {
;     ...
;       for (int s = 0; s < 2; ++s) {
;         const bf16x8 af = *reinterpret_cast<const bf16x8*>(&sm_uc[(sb * 64 + wid * 16 + (lane & 15)) * LDSS + s * 32 + (lane >> 4) * 8]);
; #pragma unroll
;         for (int t = 0; t < 8; ++t) {
;           const bf16x8 bfr = *reinterpret_cast<const bf16x8*>(&sm_w[(t * 16 + (lane & 15)) * LDSS + s * 32 + (lane >> 4) * 8]);
;           acc[t] = __builtin_amdgcn_mfma_f32_16x16x32_bf16(af, bfr, acc[t], 0, 0, 0);
;         }
;       }
; #pragma unroll
;       for (int tc = 0; tc < 4; ++tc)
; #pragma unroll
;         for (int reg = 0; reg < 4; ++reg) {
;           const int tl = wid * 16 + (lane >> 4) * 4 + reg;
;           const int c = 16 * tc + (lane & 15);
;           const float r = __builtin_amdgcn_rcpf(1.f + __builtin_amdgcn_exp2f(acc[tc][reg] + ba[tc]));
;           const float ii = __builtin_amdgcn_rcpf(1.f + __builtin_amdgcn_exp2f(acc[tc + 4][reg] + bi[tc]));
;           const float la = -c8[tc] * r;
;           const float a = __builtin_amdgcn_exp2f(la);
;           const float ucv = bf2f(sm_uc[(sb * 64 + tl) * LDSS + c]);
;           const float bt = __builtin_amdgcn_sqrtf(fmaxf(1.f - a * a, 0.f)) * (ii * ucv);
;           sm_a[tl * 64 + c] = a;
;           sm_b[tl * 64 + c] = bt;
;         }
	v_mfma_f32_16x16x32_bf16 v[24:27], v[76:79], v[238:241], 0
	v_mfma_f32_16x16x32_bf16 v[114:117], v[76:79], v[246:249], 0
	s_waitcnt lgkmcnt(2)
	v_mfma_f32_16x16x32_bf16 v[24:27], v[80:83], v[242:245], v[24:27]
	v_mfma_f32_16x16x32_bf16 v[114:117], v[80:83], v[194:197], v[114:117]
	s_waitcnt lgkmcnt(1)
	v_mfma_f32_16x16x32_bf16 v[28:31], v[122:125], v[238:241], 0
	v_mfma_f32_16x16x32_bf16 v[118:121], v[122:125], v[246:249], 0
	s_waitcnt lgkmcnt(0)
	v_mfma_f32_16x16x32_bf16 v[28:31], v[126:129], v[242:245], v[28:31]
	v_mfma_f32_16x16x32_bf16 v[118:121], v[126:129], v[194:197], v[118:121]
	s_lshl_b32 s0, s56, 8
	s_add_u32 s0, s0, 0x0
	s_add_u32 s4, s20, s0
	s_addc_u32 s5, s21, 0
	global_load_dwordx4 v[238:241], v251, s[4:5]
	global_load_dwordx4 v[242:245], v251, s[4:5] offset:64
	s_add_u32 s4, s4, 0x2000
	s_addc_u32 s5, s5, 0
	global_load_dwordx4 v[246:249], v251, s[4:5]
	global_load_dwordx4 v[194:197], v251, s[4:5] offset:64
	s_nop 7
	s_nop 7
	v_add_f32_e32 v0, v0, v145
	v_add_f32_e32 v1, v1, v145
	v_add_f32_e32 v2, v2, v145
	v_add_f32_e32 v3, v3, v145
	v_add_f32_e32 v90, v90, v146
	v_add_f32_e32 v91, v91, v146
	v_add_f32_e32 v92, v92, v146
	v_add_f32_e32 v93, v93, v146
	v_exp_f32_e32 v0, v0
	v_exp_f32_e32 v1, v1
	v_exp_f32_e32 v2, v2
	v_exp_f32_e32 v3, v3
	v_exp_f32_e32 v90, v90
	v_exp_f32_e32 v91, v91
	v_exp_f32_e32 v92, v92
	v_exp_f32_e32 v93, v93
	v_add_f32_e32 v0, 1.0, v0
	v_add_f32_e32 v1, 1.0, v1
	v_add_f32_e32 v2, 1.0, v2
	v_add_f32_e32 v3, 1.0, v3
	v_add_f32_e32 v90, 1.0, v90
	v_add_f32_e32 v91, 1.0, v91
	v_add_f32_e32 v92, 1.0, v92
	v_add_f32_e32 v93, 1.0, v93
	v_rcp_f32_e32 v0, v0
	v_rcp_f32_e32 v1, v1
	v_rcp_f32_e32 v2, v2
	v_rcp_f32_e32 v3, v3
	v_rcp_f32_e32 v90, v90
	v_rcp_f32_e32 v91, v91
	v_rcp_f32_e32 v92, v92
	v_rcp_f32_e32 v93, v93
	v_mul_f32_e32 v0, v147, v0
	v_mul_f32_e32 v1, v147, v1
	v_mul_f32_e32 v2, v147, v2
	v_mul_f32_e32 v3, v147, v3
	v_mul_f32_e32 v90, v90, v162
	v_mul_f32_e32 v91, v91, v163
	v_mul_f32_e32 v92, v92, v164
	v_mul_f32_e32 v93, v93, v165
	v_exp_f32_e32 v0, v0
	v_exp_f32_e32 v1, v1
	v_exp_f32_e32 v2, v2
	v_exp_f32_e32 v3, v3
	s_nop 0
	v_fma_f32 v138, -v0, v0, 1.0 clamp
	v_fma_f32 v139, -v1, v1, 1.0 clamp
	v_fma_f32 v140, -v2, v2, 1.0 clamp
	v_fma_f32 v141, -v3, v3, 1.0 clamp
	v_sqrt_f32_e32 v138, v138
	v_sqrt_f32_e32 v139, v139
	v_sqrt_f32_e32 v140, v140
	v_sqrt_f32_e32 v141, v141
	s_nop 0
	v_mul_f32_e32 v90, v138, v90
	v_mul_f32_e32 v91, v139, v91
	v_mul_f32_e32 v92, v140, v92
	v_mul_f32_e32 v93, v141, v93
	v_add_f32_e32 v4, v4, v145
	v_add_f32_e32 v5, v5, v145
	v_add_f32_e32 v6, v6, v145
	v_add_f32_e32 v7, v7, v145
	v_add_f32_e32 v94, v94, v146
	v_add_f32_e32 v95, v95, v146
	v_add_f32_e32 v96, v96, v146
	v_add_f32_e32 v97, v97, v146
	v_exp_f32_e32 v4, v4
	v_exp_f32_e32 v5, v5
	v_exp_f32_e32 v6, v6
	v_exp_f32_e32 v7, v7
	v_exp_f32_e32 v94, v94
	v_exp_f32_e32 v95, v95
	v_exp_f32_e32 v96, v96
	v_exp_f32_e32 v97, v97
	v_add_f32_e32 v4, 1.0, v4
	v_add_f32_e32 v5, 1.0, v5
	v_add_f32_e32 v6, 1.0, v6
	v_add_f32_e32 v7, 1.0, v7
	v_add_f32_e32 v94, 1.0, v94
	v_add_f32_e32 v95, 1.0, v95
	v_add_f32_e32 v96, 1.0, v96
	v_add_f32_e32 v97, 1.0, v97
	v_rcp_f32_e32 v4, v4
	v_rcp_f32_e32 v5, v5
	v_rcp_f32_e32 v6, v6
	v_rcp_f32_e32 v7, v7
	v_rcp_f32_e32 v94, v94
	v_rcp_f32_e32 v95, v95
	v_rcp_f32_e32 v96, v96
	v_rcp_f32_e32 v97, v97
	v_mul_f32_e32 v4, v147, v4
	v_mul_f32_e32 v5, v147, v5
	v_mul_f32_e32 v6, v147, v6
	v_mul_f32_e32 v7, v147, v7
	v_mul_f32_e32 v94, v94, v166
	v_mul_f32_e32 v95, v95, v167
	v_mul_f32_e32 v96, v96, v168
	v_mul_f32_e32 v97, v97, v169
	v_exp_f32_e32 v4, v4
	v_exp_f32_e32 v5, v5
	v_exp_f32_e32 v6, v6
	v_exp_f32_e32 v7, v7
	s_nop 0
	v_fma_f32 v138, -v4, v4, 1.0 clamp
	v_fma_f32 v139, -v5, v5, 1.0 clamp
	v_fma_f32 v140, -v6, v6, 1.0 clamp
	v_fma_f32 v141, -v7, v7, 1.0 clamp
	v_sqrt_f32_e32 v138, v138
	v_sqrt_f32_e32 v139, v139
	v_sqrt_f32_e32 v140, v140
	v_sqrt_f32_e32 v141, v141
	s_nop 0
	v_mul_f32_e32 v94, v138, v94
	v_mul_f32_e32 v95, v139, v95
	v_mul_f32_e32 v96, v140, v96
	v_mul_f32_e32 v97, v141, v97
	v_add_f32_e32 v8, v8, v145
	v_add_f32_e32 v9, v9, v145
	v_add_f32_e32 v10, v10, v145
	v_add_f32_e32 v11, v11, v145
	v_add_f32_e32 v98, v98, v146
	v_add_f32_e32 v99, v99, v146
	v_add_f32_e32 v100, v100, v146
	v_add_f32_e32 v101, v101, v146
	v_exp_f32_e32 v8, v8
	v_exp_f32_e32 v9, v9
	v_exp_f32_e32 v10, v10
	v_exp_f32_e32 v11, v11
	v_exp_f32_e32 v98, v98
	v_exp_f32_e32 v99, v99
	v_exp_f32_e32 v100, v100
	v_exp_f32_e32 v101, v101
	v_add_f32_e32 v8, 1.0, v8
	v_add_f32_e32 v9, 1.0, v9
	v_add_f32_e32 v10, 1.0, v10
	v_add_f32_e32 v11, 1.0, v11
	v_add_f32_e32 v98, 1.0, v98
	v_add_f32_e32 v99, 1.0, v99
	v_add_f32_e32 v100, 1.0, v100
	v_add_f32_e32 v101, 1.0, v101
	v_rcp_f32_e32 v8, v8
	v_rcp_f32_e32 v9, v9
	v_rcp_f32_e32 v10, v10
	v_rcp_f32_e32 v11, v11
	v_rcp_f32_e32 v98, v98
	v_rcp_f32_e32 v99, v99
	v_rcp_f32_e32 v100, v100
	v_rcp_f32_e32 v101, v101
	v_mul_f32_e32 v8, v147, v8
	v_mul_f32_e32 v9, v147, v9
	v_mul_f32_e32 v10, v147, v10
	v_mul_f32_e32 v11, v147, v11
	v_mul_f32_e32 v98, v98, v170
	v_mul_f32_e32 v99, v99, v171
	v_mul_f32_e32 v100, v100, v172
	v_mul_f32_e32 v101, v101, v173
	v_exp_f32_e32 v8, v8
	v_exp_f32_e32 v9, v9
	v_exp_f32_e32 v10, v10
	v_exp_f32_e32 v11, v11
	s_nop 0
	v_fma_f32 v138, -v8, v8, 1.0 clamp
	v_fma_f32 v139, -v9, v9, 1.0 clamp
	v_fma_f32 v140, -v10, v10, 1.0 clamp
	v_fma_f32 v141, -v11, v11, 1.0 clamp
	v_sqrt_f32_e32 v138, v138
	v_sqrt_f32_e32 v139, v139
	v_sqrt_f32_e32 v140, v140
	v_sqrt_f32_e32 v141, v141
	s_nop 0
	v_mul_f32_e32 v98, v138, v98
	v_mul_f32_e32 v99, v139, v99
	v_mul_f32_e32 v100, v140, v100
	v_mul_f32_e32 v101, v141, v101
	v_add_f32_e32 v12, v12, v145
; __device__ __forceinline__ float bf2f(u16 h) { return __uint_as_float(((unsigned)h) << 16); }
; __device__ __forceinline__ void lru_tile(const Params& P, int chunk, int head, int pass, char* smem_raw) {
;     ...
;       for (int tc = 0; tc < 4; ++tc)
; #pragma unroll
;         for (int reg = 0; reg < 4; ++reg) {
;           const int tl = wid * 16 + (lane >> 4) * 4 + reg;
;           const int c = 16 * tc + (lane & 15);
;           const float r = __builtin_amdgcn_rcpf(1.f + __builtin_amdgcn_exp2f(acc[tc][reg] + ba[tc]));
;           const float ii = __builtin_amdgcn_rcpf(1.f + __builtin_amdgcn_exp2f(acc[tc + 4][reg] + bi[tc]));
;           const float la = -c8[tc] * r;
;           const float a = __builtin_amdgcn_exp2f(la);
;           const float ucv = bf2f(sm_uc[(sb * 64 + tl) * LDSS + c]);
;           const float bt = __builtin_amdgcn_sqrtf(fmaxf(1.f - a * a, 0.f)) * (ii * ucv);
;           sm_a[tl * 64 + c] = a;
;           sm_b[tl * 64 + c] = bt;
;         }
	v_add_f32_e32 v13, v13, v145
	v_add_f32_e32 v14, v14, v145
	v_add_f32_e32 v15, v15, v145
	v_add_f32_e32 v102, v102, v146
	v_add_f32_e32 v103, v103, v146
	v_add_f32_e32 v104, v104, v146
	v_add_f32_e32 v105, v105, v146
	v_exp_f32_e32 v12, v12
	v_exp_f32_e32 v13, v13
	v_exp_f32_e32 v14, v14
	v_exp_f32_e32 v15, v15
	v_exp_f32_e32 v102, v102
	v_exp_f32_e32 v103, v103
	v_exp_f32_e32 v104, v104
	v_exp_f32_e32 v105, v105
	v_add_f32_e32 v12, 1.0, v12
	v_add_f32_e32 v13, 1.0, v13
	v_add_f32_e32 v14, 1.0, v14
	v_add_f32_e32 v15, 1.0, v15
	v_add_f32_e32 v102, 1.0, v102
	v_add_f32_e32 v103, 1.0, v103
	v_add_f32_e32 v104, 1.0, v104
	v_add_f32_e32 v105, 1.0, v105
	v_rcp_f32_e32 v12, v12
	v_rcp_f32_e32 v13, v13
	v_rcp_f32_e32 v14, v14
	v_rcp_f32_e32 v15, v15
	v_rcp_f32_e32 v102, v102
	v_rcp_f32_e32 v103, v103
	v_rcp_f32_e32 v104, v104
	v_rcp_f32_e32 v105, v105
	v_mul_f32_e32 v12, v147, v12
	v_mul_f32_e32 v13, v147, v13
	v_mul_f32_e32 v14, v147, v14
	v_mul_f32_e32 v15, v147, v15
	v_mul_f32_e32 v102, v102, v174
	v_mul_f32_e32 v103, v103, v175
	v_mul_f32_e32 v104, v104, v176
	v_mul_f32_e32 v105, v105, v177
	v_exp_f32_e32 v12, v12
	v_exp_f32_e32 v13, v13
	v_exp_f32_e32 v14, v14
	v_exp_f32_e32 v15, v15
	s_nop 0
	v_fma_f32 v138, -v12, v12, 1.0 clamp
	v_fma_f32 v139, -v13, v13, 1.0 clamp
	v_fma_f32 v140, -v14, v14, 1.0 clamp
	v_fma_f32 v141, -v15, v15, 1.0 clamp
	v_sqrt_f32_e32 v138, v138
	v_sqrt_f32_e32 v139, v139
	v_sqrt_f32_e32 v140, v140
	v_sqrt_f32_e32 v141, v141
	s_nop 0
	v_mul_f32_e32 v102, v138, v102
	v_mul_f32_e32 v103, v139, v103
	v_mul_f32_e32 v104, v140, v104
	v_mul_f32_e32 v105, v141, v105
	v_add_f32_e32 v16, v16, v145
	v_add_f32_e32 v17, v17, v145
	v_add_f32_e32 v18, v18, v145
	v_add_f32_e32 v19, v19, v145
	v_add_f32_e32 v106, v106, v146
	v_add_f32_e32 v107, v107, v146
	v_add_f32_e32 v108, v108, v146
	v_add_f32_e32 v109, v109, v146
	v_exp_f32_e32 v16, v16
	v_exp_f32_e32 v17, v17
	v_exp_f32_e32 v18, v18
	v_exp_f32_e32 v19, v19
	v_exp_f32_e32 v106, v106
	v_exp_f32_e32 v107, v107
	v_exp_f32_e32 v108, v108
	v_exp_f32_e32 v109, v109
	v_add_f32_e32 v16, 1.0, v16
	v_add_f32_e32 v17, 1.0, v17
	v_add_f32_e32 v18, 1.0, v18
	v_add_f32_e32 v19, 1.0, v19
	v_add_f32_e32 v106, 1.0, v106
	v_add_f32_e32 v107, 1.0, v107
	v_add_f32_e32 v108, 1.0, v108
	v_add_f32_e32 v109, 1.0, v109
	v_rcp_f32_e32 v16, v16
	v_rcp_f32_e32 v17, v17
	v_rcp_f32_e32 v18, v18
	v_rcp_f32_e32 v19, v19
	v_rcp_f32_e32 v106, v106
	v_rcp_f32_e32 v107, v107
	v_rcp_f32_e32 v108, v108
	v_rcp_f32_e32 v109, v109
	v_mul_f32_e32 v16, v147, v16
	v_mul_f32_e32 v17, v147, v17
	v_mul_f32_e32 v18, v147, v18
	v_mul_f32_e32 v19, v147, v19
	v_mul_f32_e32 v106, v106, v178
	v_mul_f32_e32 v107, v107, v179
	v_mul_f32_e32 v108, v108, v180
	v_mul_f32_e32 v109, v109, v181
	v_exp_f32_e32 v16, v16
	v_exp_f32_e32 v17, v17
	v_exp_f32_e32 v18, v18
	v_exp_f32_e32 v19, v19
	s_nop 0
	v_fma_f32 v138, -v16, v16, 1.0 clamp
	v_fma_f32 v139, -v17, v17, 1.0 clamp
	v_fma_f32 v140, -v18, v18, 1.0 clamp
	v_fma_f32 v141, -v19, v19, 1.0 clamp
	v_sqrt_f32_e32 v138, v138
	v_sqrt_f32_e32 v139, v139
	v_sqrt_f32_e32 v140, v140
	v_sqrt_f32_e32 v141, v141
	s_nop 0
	v_mul_f32_e32 v106, v138, v106
	v_mul_f32_e32 v107, v139, v107
	v_mul_f32_e32 v108, v140, v108
	v_mul_f32_e32 v109, v141, v109
	v_add_f32_e32 v20, v20, v145
	v_add_f32_e32 v21, v21, v145
	v_add_f32_e32 v22, v22, v145
	v_add_f32_e32 v23, v23, v145
	v_add_f32_e32 v110, v110, v146
	v_add_f32_e32 v111, v111, v146
	v_add_f32_e32 v112, v112, v146
	v_add_f32_e32 v113, v113, v146
	v_exp_f32_e32 v20, v20
	v_exp_f32_e32 v21, v21
	v_exp_f32_e32 v22, v22
	v_exp_f32_e32 v23, v23
	v_exp_f32_e32 v110, v110
	v_exp_f32_e32 v111, v111
	v_exp_f32_e32 v112, v112
	v_exp_f32_e32 v113, v113
	v_add_f32_e32 v20, 1.0, v20
	v_add_f32_e32 v21, 1.0, v21
	v_add_f32_e32 v22, 1.0, v22
	v_add_f32_e32 v23, 1.0, v23
	v_add_f32_e32 v110, 1.0, v110
	v_add_f32_e32 v111, 1.0, v111
	v_add_f32_e32 v112, 1.0, v112
	v_add_f32_e32 v113, 1.0, v113
	v_rcp_f32_e32 v20, v20
	v_rcp_f32_e32 v21, v21
	v_rcp_f32_e32 v22, v22
	v_rcp_f32_e32 v23, v23
	v_rcp_f32_e32 v110, v110
	v_rcp_f32_e32 v111, v111
	v_rcp_f32_e32 v112, v112
	v_rcp_f32_e32 v113, v113
	v_mul_f32_e32 v20, v147, v20
	v_mul_f32_e32 v21, v147, v21
	v_mul_f32_e32 v22, v147, v22
	v_mul_f32_e32 v23, v147, v23
	v_mul_f32_e32 v110, v110, v182
	v_mul_f32_e32 v111, v111, v183
	v_mul_f32_e32 v112, v112, v184
	v_mul_f32_e32 v113, v113, v185
	v_exp_f32_e32 v20, v20
	v_exp_f32_e32 v21, v21
	v_exp_f32_e32 v22, v22
	v_exp_f32_e32 v23, v23
	s_nop 0
	v_fma_f32 v138, -v20, v20, 1.0 clamp
	v_fma_f32 v139, -v21, v21, 1.0 clamp
	v_fma_f32 v140, -v22, v22, 1.0 clamp
	v_fma_f32 v141, -v23, v23, 1.0 clamp
	v_sqrt_f32_e32 v138, v138
	v_sqrt_f32_e32 v139, v139
	v_sqrt_f32_e32 v140, v140
	v_sqrt_f32_e32 v141, v141
	s_nop 0
	v_mul_f32_e32 v110, v138, v110
	v_mul_f32_e32 v111, v139, v111
	v_mul_f32_e32 v112, v140, v112
	v_mul_f32_e32 v113, v141, v113
	v_add_f32_e32 v24, v24, v145
	v_add_f32_e32 v25, v25, v145
	v_add_f32_e32 v26, v26, v145
	v_add_f32_e32 v27, v27, v145
	v_add_f32_e32 v114, v114, v146
	v_add_f32_e32 v115, v115, v146
	v_add_f32_e32 v116, v116, v146
	v_add_f32_e32 v117, v117, v146
	v_exp_f32_e32 v24, v24
	v_exp_f32_e32 v25, v25
	v_exp_f32_e32 v26, v26
	v_exp_f32_e32 v27, v27
	v_exp_f32_e32 v114, v114
	v_exp_f32_e32 v115, v115
	v_exp_f32_e32 v116, v116
	v_exp_f32_e32 v117, v117
	v_add_f32_e32 v24, 1.0, v24
	v_add_f32_e32 v25, 1.0, v25
	v_add_f32_e32 v26, 1.0, v26
	v_add_f32_e32 v27, 1.0, v27
	v_add_f32_e32 v114, 1.0, v114
	v_add_f32_e32 v115, 1.0, v115
	v_add_f32_e32 v116, 1.0, v116
	v_add_f32_e32 v117, 1.0, v117
	v_rcp_f32_e32 v24, v24
	v_rcp_f32_e32 v25, v25
	v_rcp_f32_e32 v26, v26
; __device__ __forceinline__ float bf2f(u16 h) { return __uint_as_float(((unsigned)h) << 16); }
; __device__ __forceinline__ void lru_tile(const Params& P, int chunk, int head, int pass, char* smem_raw) {
;     ...
;       for (int tc = 0; tc < 4; ++tc)
; #pragma unroll
;         for (int reg = 0; reg < 4; ++reg) {
;           const int tl = wid * 16 + (lane >> 4) * 4 + reg;
;           const int c = 16 * tc + (lane & 15);
;           const float r = __builtin_amdgcn_rcpf(1.f + __builtin_amdgcn_exp2f(acc[tc][reg] + ba[tc]));
;           const float ii = __builtin_amdgcn_rcpf(1.f + __builtin_amdgcn_exp2f(acc[tc + 4][reg] + bi[tc]));
;           const float la = -c8[tc] * r;
;           const float a = __builtin_amdgcn_exp2f(la);
;           const float ucv = bf2f(sm_uc[(sb * 64 + tl) * LDSS + c]);
;           const float bt = __builtin_amdgcn_sqrtf(fmaxf(1.f - a * a, 0.f)) * (ii * ucv);
;           sm_a[tl * 64 + c] = a;
;           sm_b[tl * 64 + c] = bt;
;         }
;     ...
;         if (d == 1) {
; #pragma unroll
;           for (int i = 0; i < 16; ++i) {
;             const long rowp = row0 + sb * 64 + q * 16 + 15 - i;
;             hfp[i] = hfbuf[rowp * 512 + gch];
;             gp[i] = bf2f(P.zq[rowp * 1536 + 512 + gch]);
;           }
	v_rcp_f32_e32 v27, v27
	v_rcp_f32_e32 v114, v114
	v_rcp_f32_e32 v115, v115
	v_rcp_f32_e32 v116, v116
	v_rcp_f32_e32 v117, v117
	v_mul_f32_e32 v24, v147, v24
	v_mul_f32_e32 v25, v147, v25
	v_mul_f32_e32 v26, v147, v26
	v_mul_f32_e32 v27, v147, v27
	v_mul_f32_e32 v114, v114, v186
	v_mul_f32_e32 v115, v115, v187
	v_mul_f32_e32 v116, v116, v188
	v_mul_f32_e32 v117, v117, v189
	v_exp_f32_e32 v24, v24
	v_exp_f32_e32 v25, v25
	v_exp_f32_e32 v26, v26
	v_exp_f32_e32 v27, v27
	s_nop 0
	v_fma_f32 v138, -v24, v24, 1.0 clamp
	v_fma_f32 v139, -v25, v25, 1.0 clamp
	v_fma_f32 v140, -v26, v26, 1.0 clamp
	v_fma_f32 v141, -v27, v27, 1.0 clamp
	v_sqrt_f32_e32 v138, v138
	v_sqrt_f32_e32 v139, v139
	v_sqrt_f32_e32 v140, v140
	v_sqrt_f32_e32 v141, v141
	s_nop 0
	v_mul_f32_e32 v114, v138, v114
	v_mul_f32_e32 v115, v139, v115
	v_mul_f32_e32 v116, v140, v116
	v_mul_f32_e32 v117, v141, v117
	v_add_f32_e32 v28, v28, v145
	v_add_f32_e32 v29, v29, v145
	v_add_f32_e32 v30, v30, v145
	v_add_f32_e32 v31, v31, v145
	v_add_f32_e32 v118, v118, v146
	v_add_f32_e32 v119, v119, v146
	v_add_f32_e32 v120, v120, v146
	v_add_f32_e32 v121, v121, v146
	v_exp_f32_e32 v28, v28
	v_exp_f32_e32 v29, v29
	v_exp_f32_e32 v30, v30
	v_exp_f32_e32 v31, v31
	v_exp_f32_e32 v118, v118
	v_exp_f32_e32 v119, v119
	v_exp_f32_e32 v120, v120
	v_exp_f32_e32 v121, v121
	v_add_f32_e32 v28, 1.0, v28
	v_add_f32_e32 v29, 1.0, v29
	v_add_f32_e32 v30, 1.0, v30
	v_add_f32_e32 v31, 1.0, v31
	v_add_f32_e32 v118, 1.0, v118
	v_add_f32_e32 v119, 1.0, v119
	v_add_f32_e32 v120, 1.0, v120
	v_add_f32_e32 v121, 1.0, v121
	v_rcp_f32_e32 v28, v28
	v_rcp_f32_e32 v29, v29
	v_rcp_f32_e32 v30, v30
	v_rcp_f32_e32 v31, v31
	v_rcp_f32_e32 v118, v118
	v_rcp_f32_e32 v119, v119
	v_rcp_f32_e32 v120, v120
	v_rcp_f32_e32 v121, v121
	v_mul_f32_e32 v28, v147, v28
	v_mul_f32_e32 v29, v147, v29
	v_mul_f32_e32 v30, v147, v30
	v_mul_f32_e32 v31, v147, v31
	v_mul_f32_e32 v118, v118, v190
	v_mul_f32_e32 v119, v119, v191
	v_mul_f32_e32 v120, v120, v192
	v_mul_f32_e32 v121, v121, v193
	v_exp_f32_e32 v28, v28
	v_exp_f32_e32 v29, v29
	v_exp_f32_e32 v30, v30
	v_exp_f32_e32 v31, v31
	s_nop 0
	v_fma_f32 v138, -v28, v28, 1.0 clamp
	v_fma_f32 v139, -v29, v29, 1.0 clamp
	v_fma_f32 v140, -v30, v30, 1.0 clamp
	v_fma_f32 v141, -v31, v31, 1.0 clamp
	v_sqrt_f32_e32 v138, v138
	v_sqrt_f32_e32 v139, v139
	v_sqrt_f32_e32 v140, v140
	v_sqrt_f32_e32 v141, v141
	s_nop 0
	v_mul_f32_e32 v118, v138, v118
	v_mul_f32_e32 v119, v139, v119
	v_mul_f32_e32 v120, v140, v120
	v_mul_f32_e32 v121, v141, v121
	s_mul_i32 s0, s71, 0x60000
	s_lshl_b32 s1, s56, 1
	s_add_u32 s0, s0, s1
	s_add_u32 s0, s0, 0x400
	s_add_u32 s4, s10, s0
	s_addc_u32 s5, s11, 0
	global_load_ushort v162, v134, s[4:5]
	s_add_u32 s4, s4, 0xc00
	s_addc_u32 s5, s5, 0
	global_load_ushort v163, v134, s[4:5]
	s_add_u32 s4, s4, 0xc00
	s_addc_u32 s5, s5, 0
	global_load_ushort v164, v134, s[4:5]
	s_add_u32 s4, s4, 0xc00
	s_addc_u32 s5, s5, 0
	global_load_ushort v165, v134, s[4:5]
	s_add_u32 s4, s4, 0xc00
	s_addc_u32 s5, s5, 0
	global_load_ushort v166, v134, s[4:5]
	s_add_u32 s4, s4, 0xc00
	s_addc_u32 s5, s5, 0
	global_load_ushort v167, v134, s[4:5]
	s_add_u32 s4, s4, 0xc00
	s_addc_u32 s5, s5, 0
	global_load_ushort v168, v134, s[4:5]
	s_add_u32 s4, s4, 0xc00
	s_addc_u32 s5, s5, 0
	global_load_ushort v169, v134, s[4:5]
	s_add_u32 s4, s4, 0xc00
	s_addc_u32 s5, s5, 0
	global_load_ushort v170, v134, s[4:5]
	s_add_u32 s4, s4, 0xc00
	s_addc_u32 s5, s5, 0
	global_load_ushort v171, v134, s[4:5]
	s_add_u32 s4, s4, 0xc00
	s_addc_u32 s5, s5, 0
	global_load_ushort v172, v134, s[4:5]
	s_add_u32 s4, s4, 0xc00
	s_addc_u32 s5, s5, 0
	global_load_ushort v173, v134, s[4:5]
	s_add_u32 s4, s4, 0xc00
	s_addc_u32 s5, s5, 0
	global_load_ushort v174, v134, s[4:5]
	s_add_u32 s4, s4, 0xc00
	s_addc_u32 s5, s5, 0
	global_load_ushort v175, v134, s[4:5]
	s_add_u32 s4, s4, 0xc00
	s_addc_u32 s5, s5, 0
	global_load_ushort v176, v134, s[4:5]
	s_add_u32 s4, s4, 0xc00
	s_addc_u32 s5, s5, 0
	global_load_ushort v177, v134, s[4:5]
	s_add_u32 s4, s4, 0xc00
	s_addc_u32 s5, s5, 0
	global_load_ushort v178, v134, s[4:5]
	s_add_u32 s4, s4, 0xc00
	s_addc_u32 s5, s5, 0
	global_load_ushort v179, v134, s[4:5]
	s_add_u32 s4, s4, 0xc00
	s_addc_u32 s5, s5, 0
	global_load_ushort v180, v134, s[4:5]
	s_add_u32 s4, s4, 0xc00
	s_addc_u32 s5, s5, 0
	global_load_ushort v181, v134, s[4:5]
	s_add_u32 s4, s4, 0xc00
	s_addc_u32 s5, s5, 0
	global_load_ushort v182, v134, s[4:5]
	s_add_u32 s4, s4, 0xc00
	s_addc_u32 s5, s5, 0
	global_load_ushort v183, v134, s[4:5]
	s_add_u32 s4, s4, 0xc00
	s_addc_u32 s5, s5, 0
	global_load_ushort v184, v134, s[4:5]
	s_add_u32 s4, s4, 0xc00
	s_addc_u32 s5, s5, 0
	global_load_ushort v185, v134, s[4:5]
	s_add_u32 s4, s4, 0xc00
	s_addc_u32 s5, s5, 0
	global_load_ushort v186, v134, s[4:5]
	s_add_u32 s4, s4, 0xc00
	s_addc_u32 s5, s5, 0
	global_load_ushort v187, v134, s[4:5]
	s_add_u32 s4, s4, 0xc00
	s_addc_u32 s5, s5, 0
	global_load_ushort v188, v134, s[4:5]
	s_add_u32 s4, s4, 0xc00
	s_addc_u32 s5, s5, 0
	global_load_ushort v189, v134, s[4:5]
	s_add_u32 s4, s4, 0xc00
	s_addc_u32 s5, s5, 0
	global_load_ushort v190, v134, s[4:5]
	s_add_u32 s4, s4, 0xc00
	s_addc_u32 s5, s5, 0
	global_load_ushort v191, v134, s[4:5]
	s_add_u32 s4, s4, 0xc00
	s_addc_u32 s5, s5, 0
	global_load_ushort v192, v134, s[4:5]
	s_add_u32 s4, s4, 0xc00
	s_addc_u32 s5, s5, 0
	global_load_ushort v193, v134, s[4:5]
	v_mov_b32_e32 v253, v31
	v_mov_b32_e32 v254, v121
	v_fma_f32 v254, v30, v254, v120
	v_mul_f32_e32 v253, v253, v30
	v_fma_f32 v254, v29, v254, v119
	v_mul_f32_e32 v253, v253, v29
	v_fma_f32 v254, v28, v254, v118
	v_mul_f32_e32 v253, v253, v28
	v_fma_f32 v254, v27, v254, v117
; __device__ __forceinline__ float bf2f(u16 h) { return __uint_as_float(((unsigned)h) << 16); }
; __device__ __forceinline__ void lru_tile(const Params& P, int chunk, int head, int pass, char* smem_raw) {
;     ...
;       {
;         float Pp = 1.f, H = 0.f;
; #pragma unroll 4
;         for (int i = 0; i < 16; ++i) {
;           const int tl = (d == 0) ? (q * 16 + i) : (q * 16 + 15 - i);
;           const float a = sm_a[tl * 64 + ch], b = sm_b[tl * 64 + ch];
;           H = a * H + b; Pp *= a;
;         }
;         sm_ph[pos * 64 + ch] = make_float2(Pp, H);
;       }
;       __syncthreads();
;       const float2 p0 = sm_ph[ch], p1 = sm_ph[64 + ch], p2 = sm_ph[128 + ch], p3 = sm_ph[192 + ch];
;       if (pass == 2) {
;         float hin = cB;
;         if (pos > 0) hin = p0.x * hin + p0.y;
;         if (pos > 1) hin = p1.x * hin + p1.y;
;         if (pos > 2) hin = p2.x * hin + p2.y;
;         float h = hin;
;         float hfp[16], gp[16];
;         if (d == 1) {
; #pragma unroll
;           for (int i = 0; i < 16; ++i) {
;             const long rowp = row0 + sb * 64 + q * 16 + 15 - i;
;             hfp[i] = hfbuf[rowp * 512 + gch];
;             gp[i] = bf2f(P.zq[rowp * 1536 + 512 + gch]);
;           }
;         }
; #pragma unroll
;         for (int i = 0; i < 16; ++i) {
;           const int tl = (d == 0) ? (q * 16 + i) : (q * 16 + 15 - i);
;           const float a = sm_a[tl * 64 + ch], b = sm_b[tl * 64 + ch];
;           h = a * h + b;
;           const long row = row0 + sb * 64 + tl;
;           if (d == 0) {
;             hfw[row * 512 + gch] = h;
;           } else {
;             const float hfv = hfp[i];
;             const float g = gp[i];
;             const float tz = 0.7978845608028654f * (g + 0.044715f * g * g * g);
;             const float th = 1.f - 2.f * __builtin_amdgcn_rcpf(1.f + __expf(2.f * tz));
;             const float ge = 0.5f * g * (1.f + th);
;             P.cat[row * 1024 + gch] = f2bf((hfv + h) * ge);
	v_mul_f32_e32 v253, v253, v27
	v_fma_f32 v254, v26, v254, v116
	v_mul_f32_e32 v253, v253, v26
	v_fma_f32 v254, v25, v254, v115
	v_mul_f32_e32 v253, v253, v25
	v_fma_f32 v254, v24, v254, v114
	v_mul_f32_e32 v253, v253, v24
	v_fma_f32 v254, v23, v254, v113
	v_mul_f32_e32 v253, v253, v23
	v_fma_f32 v254, v22, v254, v112
	v_mul_f32_e32 v253, v253, v22
	v_fma_f32 v254, v21, v254, v111
	v_mul_f32_e32 v253, v253, v21
	v_fma_f32 v254, v20, v254, v110
	v_mul_f32_e32 v253, v253, v20
	v_fma_f32 v254, v19, v254, v109
	v_mul_f32_e32 v253, v253, v19
	v_fma_f32 v254, v18, v254, v108
	v_mul_f32_e32 v253, v253, v18
	v_fma_f32 v254, v17, v254, v107
	v_mul_f32_e32 v253, v253, v17
	v_fma_f32 v254, v16, v254, v106
	v_mul_f32_e32 v253, v253, v16
	v_fma_f32 v254, v15, v254, v105
	v_mul_f32_e32 v253, v253, v15
	v_fma_f32 v254, v14, v254, v104
	v_mul_f32_e32 v253, v253, v14
	v_fma_f32 v254, v13, v254, v103
	v_mul_f32_e32 v253, v253, v13
	v_fma_f32 v254, v12, v254, v102
	v_mul_f32_e32 v253, v253, v12
	v_fma_f32 v254, v11, v254, v101
	v_mul_f32_e32 v253, v253, v11
	v_fma_f32 v254, v10, v254, v100
	v_mul_f32_e32 v253, v253, v10
	v_fma_f32 v254, v9, v254, v99
	v_mul_f32_e32 v253, v253, v9
	v_fma_f32 v254, v8, v254, v98
	v_mul_f32_e32 v253, v253, v8
	v_fma_f32 v254, v7, v254, v97
	v_mul_f32_e32 v253, v253, v7
	v_fma_f32 v254, v6, v254, v96
	v_mul_f32_e32 v253, v253, v6
	v_fma_f32 v254, v5, v254, v95
	v_mul_f32_e32 v253, v253, v5
	v_fma_f32 v254, v4, v254, v94
	v_mul_f32_e32 v253, v253, v4
	v_fma_f32 v254, v3, v254, v93
	v_mul_f32_e32 v253, v253, v3
	v_fma_f32 v254, v2, v254, v92
	v_mul_f32_e32 v253, v253, v2
	v_fma_f32 v254, v1, v254, v91
	v_mul_f32_e32 v253, v253, v1
	v_fma_f32 v254, v0, v254, v90
	v_mul_f32_e32 v253, v253, v0
	v_mov_b32_e32 v138, v253
	v_mov_b32_e32 v139, v253
	s_nop 1
	v_permlane16_swap_b32_e32 v138, v139
	v_mov_b32_e32 v140, v138
	v_mov_b32_e32 v141, v139
	s_nop 1
	v_permlane32_swap_b32_e32 v138, v140
	v_permlane32_swap_b32_e32 v139, v141
	v_mov_b32_e32 v198, v254
	v_mov_b32_e32 v199, v254
	s_nop 1
	v_permlane16_swap_b32_e32 v198, v199
	v_mov_b32_e32 v200, v198
	v_mov_b32_e32 v201, v199
	s_nop 1
	v_permlane32_swap_b32_e32 v198, v200
	v_permlane32_swap_b32_e32 v199, v201
	v_mov_b32_e32 v202, v149
	v_fma_f32 v151, v141, v202, v201
	v_fma_f32 v150, v140, v151, v200
	v_fma_f32 v136, v139, v150, v199
	v_mov_b32_e32 v254, v202
	v_cndmask_b32_e64 v254, v254, v151, s[78:79]
	v_cndmask_b32_e64 v254, v254, v150, s[80:81]
	v_cndmask_b32_e64 v254, v254, v136, s[82:83]
	v_fma_f32 v121, v31, v254, v121
	v_fma_f32 v120, v30, v121, v120
	v_fma_f32 v119, v29, v120, v119
	v_fma_f32 v118, v28, v119, v118
	v_fma_f32 v117, v27, v118, v117
	v_fma_f32 v116, v26, v117, v116
	v_fma_f32 v115, v25, v116, v115
	v_fma_f32 v114, v24, v115, v114
	v_fma_f32 v113, v23, v114, v113
	v_fma_f32 v112, v22, v113, v112
	v_fma_f32 v111, v21, v112, v111
	v_fma_f32 v110, v20, v111, v110
	v_fma_f32 v109, v19, v110, v109
	v_fma_f32 v108, v18, v109, v108
	v_fma_f32 v107, v17, v108, v107
	v_fma_f32 v106, v16, v107, v106
	v_fma_f32 v105, v15, v106, v105
	v_fma_f32 v104, v14, v105, v104
	v_fma_f32 v103, v13, v104, v103
	v_fma_f32 v102, v12, v103, v102
	v_fma_f32 v101, v11, v102, v101
	v_fma_f32 v100, v10, v101, v100
	v_fma_f32 v99, v9, v100, v99
	v_fma_f32 v98, v8, v99, v98
	v_fma_f32 v97, v7, v98, v97
	v_fma_f32 v96, v6, v97, v96
	v_fma_f32 v95, v5, v96, v95
	v_fma_f32 v94, v4, v95, v94
	v_fma_f32 v93, v3, v94, v93
	v_fma_f32 v92, v2, v93, v92
	v_fma_f32 v91, v1, v92, v91
	v_fma_f32 v90, v0, v91, v90
	s_waitcnt vmcnt(0)
	v_lshlrev_b32_e32 v162, 16, v162
	v_lshlrev_b32_e32 v163, 16, v163
	v_lshlrev_b32_e32 v164, 16, v164
	v_lshlrev_b32_e32 v165, 16, v165
	v_lshlrev_b32_e32 v166, 16, v166
	v_lshlrev_b32_e32 v167, 16, v167
	v_lshlrev_b32_e32 v168, 16, v168
	v_lshlrev_b32_e32 v169, 16, v169
	v_lshlrev_b32_e32 v170, 16, v170
	v_lshlrev_b32_e32 v171, 16, v171
	v_lshlrev_b32_e32 v172, 16, v172
	v_lshlrev_b32_e32 v173, 16, v173
	v_lshlrev_b32_e32 v174, 16, v174
	v_lshlrev_b32_e32 v175, 16, v175
	v_lshlrev_b32_e32 v176, 16, v176
	v_lshlrev_b32_e32 v177, 16, v177
	v_lshlrev_b32_e32 v178, 16, v178
	v_lshlrev_b32_e32 v179, 16, v179
	v_lshlrev_b32_e32 v180, 16, v180
	v_lshlrev_b32_e32 v181, 16, v181
	v_lshlrev_b32_e32 v182, 16, v182
	v_lshlrev_b32_e32 v183, 16, v183
	v_lshlrev_b32_e32 v184, 16, v184
	v_lshlrev_b32_e32 v185, 16, v185
	v_lshlrev_b32_e32 v186, 16, v186
	v_lshlrev_b32_e32 v187, 16, v187
	v_lshlrev_b32_e32 v188, 16, v188
	v_lshlrev_b32_e32 v189, 16, v189
	v_lshlrev_b32_e32 v190, 16, v190
	v_lshlrev_b32_e32 v191, 16, v191
	v_lshlrev_b32_e32 v192, 16, v192
	v_lshlrev_b32_e32 v193, 16, v193
	v_mov_b32_e32 v202, 0x3d372713
	v_mul_f32_e32 v138, v162, v162
	v_mul_f32_e32 v139, v163, v163
	v_mul_f32_e32 v140, v164, v164
	v_mul_f32_e32 v141, v165, v165
	v_mul_f32_e32 v138, v138, v162
	v_mul_f32_e32 v139, v139, v163
	v_mul_f32_e32 v140, v140, v164
	v_mul_f32_e32 v141, v141, v165
	v_fma_f32 v138, v202, v138, v162
	v_fma_f32 v139, v202, v139, v163
	v_fma_f32 v140, v202, v140, v164
	v_fma_f32 v141, v202, v141, v165
	v_mul_f32_e32 v138, 0x40135761, v138
	v_mul_f32_e32 v139, 0x40135761, v139
	v_mul_f32_e32 v140, 0x40135761, v140
	v_mul_f32_e32 v141, 0x40135761, v141
	v_exp_f32_e32 v138, v138
	v_exp_f32_e32 v139, v139
	v_exp_f32_e32 v140, v140
	v_exp_f32_e32 v141, v141
	s_nop 0
	v_add_f32_e32 v138, 1.0, v138
	v_add_f32_e32 v139, 1.0, v139
	v_add_f32_e32 v140, 1.0, v140
	v_add_f32_e32 v141, 1.0, v141
	v_rcp_f32_e32 v138, v138
	v_rcp_f32_e32 v139, v139
	v_rcp_f32_e32 v140, v140
	v_rcp_f32_e32 v141, v141
	s_nop 0
	v_fma_f32 v138, -2.0, v138, 1.0
	v_fma_f32 v139, -2.0, v139, 1.0
	v_fma_f32 v140, -2.0, v140, 1.0
; __device__ __forceinline__ void lru_tile(const Params& P, int chunk, int head, int pass, char* smem_raw) {
;     ...
;           } else {
;             const float hfv = hfp[i];
;             const float g = gp[i];
;             const float tz = 0.7978845608028654f * (g + 0.044715f * g * g * g);
;             const float th = 1.f - 2.f * __builtin_amdgcn_rcpf(1.f + __expf(2.f * tz));
;             const float ge = 0.5f * g * (1.f + th);
;             P.cat[row * 1024 + gch] = f2bf((hfv + h) * ge);
;           }
	v_fma_f32 v141, -2.0, v141, 1.0
	v_add_f32_e32 v138, 1.0, v138
	v_add_f32_e32 v139, 1.0, v139
	v_add_f32_e32 v140, 1.0, v140
	v_add_f32_e32 v141, 1.0, v141
	v_mul_f32_e32 v162, 0.5, v162
	v_mul_f32_e32 v163, 0.5, v163
	v_mul_f32_e32 v164, 0.5, v164
	v_mul_f32_e32 v165, 0.5, v165
	v_mul_f32_e32 v162, v162, v138
	v_mul_f32_e32 v163, v163, v139
	v_mul_f32_e32 v164, v164, v140
	v_mul_f32_e32 v165, v165, v141
	v_add_f32_e32 v90, v205, v90
	v_add_f32_e32 v91, v206, v91
	v_add_f32_e32 v92, v207, v92
	v_add_f32_e32 v93, v208, v93
	v_mul_f32_e32 v90, v90, v162
	v_mul_f32_e32 v91, v91, v163
	v_mul_f32_e32 v92, v92, v164
	v_mul_f32_e32 v93, v93, v165
	v_cvt_pk_bf16_f32 v90, v90, v90
	v_cvt_pk_bf16_f32 v91, v91, v91
	v_cvt_pk_bf16_f32 v92, v92, v92
	v_cvt_pk_bf16_f32 v93, v93, v93
	v_mul_f32_e32 v138, v166, v166
	v_mul_f32_e32 v139, v167, v167
	v_mul_f32_e32 v140, v168, v168
	v_mul_f32_e32 v141, v169, v169
	v_mul_f32_e32 v138, v138, v166
	v_mul_f32_e32 v139, v139, v167
	v_mul_f32_e32 v140, v140, v168
	v_mul_f32_e32 v141, v141, v169
	v_fma_f32 v138, v202, v138, v166
	v_fma_f32 v139, v202, v139, v167
	v_fma_f32 v140, v202, v140, v168
	v_fma_f32 v141, v202, v141, v169
	v_mul_f32_e32 v138, 0x40135761, v138
	v_mul_f32_e32 v139, 0x40135761, v139
	v_mul_f32_e32 v140, 0x40135761, v140
	v_mul_f32_e32 v141, 0x40135761, v141
	v_exp_f32_e32 v138, v138
	v_exp_f32_e32 v139, v139
	v_exp_f32_e32 v140, v140
	v_exp_f32_e32 v141, v141
	s_nop 0
	v_add_f32_e32 v138, 1.0, v138
	v_add_f32_e32 v139, 1.0, v139
	v_add_f32_e32 v140, 1.0, v140
	v_add_f32_e32 v141, 1.0, v141
	v_rcp_f32_e32 v138, v138
	v_rcp_f32_e32 v139, v139
	v_rcp_f32_e32 v140, v140
	v_rcp_f32_e32 v141, v141
	s_nop 0
	v_fma_f32 v138, -2.0, v138, 1.0
	v_fma_f32 v139, -2.0, v139, 1.0
	v_fma_f32 v140, -2.0, v140, 1.0
	v_fma_f32 v141, -2.0, v141, 1.0
	v_add_f32_e32 v138, 1.0, v138
	v_add_f32_e32 v139, 1.0, v139
	v_add_f32_e32 v140, 1.0, v140
	v_add_f32_e32 v141, 1.0, v141
	v_mul_f32_e32 v166, 0.5, v166
	v_mul_f32_e32 v167, 0.5, v167
	v_mul_f32_e32 v168, 0.5, v168
	v_mul_f32_e32 v169, 0.5, v169
	v_mul_f32_e32 v166, v166, v138
	v_mul_f32_e32 v167, v167, v139
	v_mul_f32_e32 v168, v168, v140
	v_mul_f32_e32 v169, v169, v141
	v_add_f32_e32 v94, v209, v94
	v_add_f32_e32 v95, v210, v95
	v_add_f32_e32 v96, v211, v96
	v_add_f32_e32 v97, v212, v97
	v_mul_f32_e32 v94, v94, v166
	v_mul_f32_e32 v95, v95, v167
	v_mul_f32_e32 v96, v96, v168
	v_mul_f32_e32 v97, v97, v169
	v_cvt_pk_bf16_f32 v94, v94, v94
	v_cvt_pk_bf16_f32 v95, v95, v95
	v_cvt_pk_bf16_f32 v96, v96, v96
	v_cvt_pk_bf16_f32 v97, v97, v97
	v_mul_f32_e32 v138, v170, v170
	v_mul_f32_e32 v139, v171, v171
	v_mul_f32_e32 v140, v172, v172
	v_mul_f32_e32 v141, v173, v173
	v_mul_f32_e32 v138, v138, v170
	v_mul_f32_e32 v139, v139, v171
	v_mul_f32_e32 v140, v140, v172
	v_mul_f32_e32 v141, v141, v173
	v_fma_f32 v138, v202, v138, v170
	v_fma_f32 v139, v202, v139, v171
	v_fma_f32 v140, v202, v140, v172
	v_fma_f32 v141, v202, v141, v173
	v_mul_f32_e32 v138, 0x40135761, v138
	v_mul_f32_e32 v139, 0x40135761, v139
	v_mul_f32_e32 v140, 0x40135761, v140
	v_mul_f32_e32 v141, 0x40135761, v141
	v_exp_f32_e32 v138, v138
	v_exp_f32_e32 v139, v139
	v_exp_f32_e32 v140, v140
	v_exp_f32_e32 v141, v141
	s_nop 0
	v_add_f32_e32 v138, 1.0, v138
	v_add_f32_e32 v139, 1.0, v139
	v_add_f32_e32 v140, 1.0, v140
	v_add_f32_e32 v141, 1.0, v141
	v_rcp_f32_e32 v138, v138
	v_rcp_f32_e32 v139, v139
	v_rcp_f32_e32 v140, v140
	v_rcp_f32_e32 v141, v141
	s_nop 0
	v_fma_f32 v138, -2.0, v138, 1.0
	v_fma_f32 v139, -2.0, v139, 1.0
	v_fma_f32 v140, -2.0, v140, 1.0
	v_fma_f32 v141, -2.0, v141, 1.0
	v_add_f32_e32 v138, 1.0, v138
	v_add_f32_e32 v139, 1.0, v139
	v_add_f32_e32 v140, 1.0, v140
	v_add_f32_e32 v141, 1.0, v141
	v_mul_f32_e32 v170, 0.5, v170
	v_mul_f32_e32 v171, 0.5, v171
	v_mul_f32_e32 v172, 0.5, v172
	v_mul_f32_e32 v173, 0.5, v173
	v_mul_f32_e32 v170, v170, v138
	v_mul_f32_e32 v171, v171, v139
	v_mul_f32_e32 v172, v172, v140
	v_mul_f32_e32 v173, v173, v141
	v_add_f32_e32 v98, v213, v98
	v_add_f32_e32 v99, v214, v99
	v_add_f32_e32 v100, v215, v100
	v_add_f32_e32 v101, v216, v101
	v_mul_f32_e32 v98, v98, v170
	v_mul_f32_e32 v99, v99, v171
	v_mul_f32_e32 v100, v100, v172
	v_mul_f32_e32 v101, v101, v173
	v_cvt_pk_bf16_f32 v98, v98, v98
	v_cvt_pk_bf16_f32 v99, v99, v99
	v_cvt_pk_bf16_f32 v100, v100, v100
	v_cvt_pk_bf16_f32 v101, v101, v101
	v_mul_f32_e32 v138, v174, v174
	v_mul_f32_e32 v139, v175, v175
	v_mul_f32_e32 v140, v176, v176
	v_mul_f32_e32 v141, v177, v177
	v_mul_f32_e32 v138, v138, v174
	v_mul_f32_e32 v139, v139, v175
	v_mul_f32_e32 v140, v140, v176
	v_mul_f32_e32 v141, v141, v177
	v_fma_f32 v138, v202, v138, v174
	v_fma_f32 v139, v202, v139, v175
	v_fma_f32 v140, v202, v140, v176
	v_fma_f32 v141, v202, v141, v177
	v_mul_f32_e32 v138, 0x40135761, v138
	v_mul_f32_e32 v139, 0x40135761, v139
	v_mul_f32_e32 v140, 0x40135761, v140
	v_mul_f32_e32 v141, 0x40135761, v141
	v_exp_f32_e32 v138, v138
	v_exp_f32_e32 v139, v139
	v_exp_f32_e32 v140, v140
	v_exp_f32_e32 v141, v141
	s_nop 0
	v_add_f32_e32 v138, 1.0, v138
	v_add_f32_e32 v139, 1.0, v139
	v_add_f32_e32 v140, 1.0, v140
	v_add_f32_e32 v141, 1.0, v141
	v_rcp_f32_e32 v138, v138
	v_rcp_f32_e32 v139, v139
	v_rcp_f32_e32 v140, v140
	v_rcp_f32_e32 v141, v141
	s_nop 0
	v_fma_f32 v138, -2.0, v138, 1.0
	v_fma_f32 v139, -2.0, v139, 1.0
	v_fma_f32 v140, -2.0, v140, 1.0
	v_fma_f32 v141, -2.0, v141, 1.0
	v_add_f32_e32 v138, 1.0, v138
	v_add_f32_e32 v139, 1.0, v139
	v_add_f32_e32 v140, 1.0, v140
	v_add_f32_e32 v141, 1.0, v141
	v_mul_f32_e32 v174, 0.5, v174
	v_mul_f32_e32 v175, 0.5, v175
	v_mul_f32_e32 v176, 0.5, v176
	v_mul_f32_e32 v177, 0.5, v177
	v_mul_f32_e32 v174, v174, v138
; __device__ __forceinline__ void lru_tile(const Params& P, int chunk, int head, int pass, char* smem_raw) {
;     ...
;           } else {
;             const float hfv = hfp[i];
;             const float g = gp[i];
;             const float tz = 0.7978845608028654f * (g + 0.044715f * g * g * g);
;             const float th = 1.f - 2.f * __builtin_amdgcn_rcpf(1.f + __expf(2.f * tz));
;             const float ge = 0.5f * g * (1.f + th);
;             P.cat[row * 1024 + gch] = f2bf((hfv + h) * ge);
;           }
	v_mul_f32_e32 v175, v175, v139
	v_mul_f32_e32 v176, v176, v140
	v_mul_f32_e32 v177, v177, v141
	v_add_f32_e32 v102, v217, v102
	v_add_f32_e32 v103, v218, v103
	v_add_f32_e32 v104, v219, v104
	v_add_f32_e32 v105, v220, v105
	v_mul_f32_e32 v102, v102, v174
	v_mul_f32_e32 v103, v103, v175
	v_mul_f32_e32 v104, v104, v176
	v_mul_f32_e32 v105, v105, v177
	v_cvt_pk_bf16_f32 v102, v102, v102
	v_cvt_pk_bf16_f32 v103, v103, v103
	v_cvt_pk_bf16_f32 v104, v104, v104
	v_cvt_pk_bf16_f32 v105, v105, v105
	v_mul_f32_e32 v138, v178, v178
	v_mul_f32_e32 v139, v179, v179
	v_mul_f32_e32 v140, v180, v180
	v_mul_f32_e32 v141, v181, v181
	v_mul_f32_e32 v138, v138, v178
	v_mul_f32_e32 v139, v139, v179
	v_mul_f32_e32 v140, v140, v180
	v_mul_f32_e32 v141, v141, v181
	v_fma_f32 v138, v202, v138, v178
	v_fma_f32 v139, v202, v139, v179
	v_fma_f32 v140, v202, v140, v180
	v_fma_f32 v141, v202, v141, v181
	v_mul_f32_e32 v138, 0x40135761, v138
	v_mul_f32_e32 v139, 0x40135761, v139
	v_mul_f32_e32 v140, 0x40135761, v140
	v_mul_f32_e32 v141, 0x40135761, v141
	v_exp_f32_e32 v138, v138
	v_exp_f32_e32 v139, v139
	v_exp_f32_e32 v140, v140
	v_exp_f32_e32 v141, v141
	s_nop 0
	v_add_f32_e32 v138, 1.0, v138
	v_add_f32_e32 v139, 1.0, v139
	v_add_f32_e32 v140, 1.0, v140
	v_add_f32_e32 v141, 1.0, v141
	v_rcp_f32_e32 v138, v138
	v_rcp_f32_e32 v139, v139
	v_rcp_f32_e32 v140, v140
	v_rcp_f32_e32 v141, v141
	s_nop 0
	v_fma_f32 v138, -2.0, v138, 1.0
	v_fma_f32 v139, -2.0, v139, 1.0
	v_fma_f32 v140, -2.0, v140, 1.0
	v_fma_f32 v141, -2.0, v141, 1.0
	v_add_f32_e32 v138, 1.0, v138
	v_add_f32_e32 v139, 1.0, v139
	v_add_f32_e32 v140, 1.0, v140
	v_add_f32_e32 v141, 1.0, v141
	v_mul_f32_e32 v178, 0.5, v178
	v_mul_f32_e32 v179, 0.5, v179
	v_mul_f32_e32 v180, 0.5, v180
	v_mul_f32_e32 v181, 0.5, v181
	v_mul_f32_e32 v178, v178, v138
	v_mul_f32_e32 v179, v179, v139
	v_mul_f32_e32 v180, v180, v140
	v_mul_f32_e32 v181, v181, v141
	v_add_f32_e32 v106, v221, v106
	v_add_f32_e32 v107, v222, v107
	v_add_f32_e32 v108, v223, v108
	v_add_f32_e32 v109, v224, v109
	v_mul_f32_e32 v106, v106, v178
	v_mul_f32_e32 v107, v107, v179
	v_mul_f32_e32 v108, v108, v180
	v_mul_f32_e32 v109, v109, v181
	v_cvt_pk_bf16_f32 v106, v106, v106
	v_cvt_pk_bf16_f32 v107, v107, v107
	v_cvt_pk_bf16_f32 v108, v108, v108
	v_cvt_pk_bf16_f32 v109, v109, v109
	v_mul_f32_e32 v138, v182, v182
	v_mul_f32_e32 v139, v183, v183
	v_mul_f32_e32 v140, v184, v184
	v_mul_f32_e32 v141, v185, v185
	v_mul_f32_e32 v138, v138, v182
	v_mul_f32_e32 v139, v139, v183
	v_mul_f32_e32 v140, v140, v184
	v_mul_f32_e32 v141, v141, v185
	v_fma_f32 v138, v202, v138, v182
	v_fma_f32 v139, v202, v139, v183
	v_fma_f32 v140, v202, v140, v184
	v_fma_f32 v141, v202, v141, v185
	v_mul_f32_e32 v138, 0x40135761, v138
	v_mul_f32_e32 v139, 0x40135761, v139
	v_mul_f32_e32 v140, 0x40135761, v140
	v_mul_f32_e32 v141, 0x40135761, v141
	v_exp_f32_e32 v138, v138
	v_exp_f32_e32 v139, v139
	v_exp_f32_e32 v140, v140
	v_exp_f32_e32 v141, v141
	s_nop 0
	v_add_f32_e32 v138, 1.0, v138
	v_add_f32_e32 v139, 1.0, v139
	v_add_f32_e32 v140, 1.0, v140
	v_add_f32_e32 v141, 1.0, v141
	v_rcp_f32_e32 v138, v138
	v_rcp_f32_e32 v139, v139
	v_rcp_f32_e32 v140, v140
	v_rcp_f32_e32 v141, v141
	s_nop 0
	v_fma_f32 v138, -2.0, v138, 1.0
	v_fma_f32 v139, -2.0, v139, 1.0
	v_fma_f32 v140, -2.0, v140, 1.0
	v_fma_f32 v141, -2.0, v141, 1.0
	v_add_f32_e32 v138, 1.0, v138
	v_add_f32_e32 v139, 1.0, v139
	v_add_f32_e32 v140, 1.0, v140
	v_add_f32_e32 v141, 1.0, v141
	v_mul_f32_e32 v182, 0.5, v182
	v_mul_f32_e32 v183, 0.5, v183
	v_mul_f32_e32 v184, 0.5, v184
	v_mul_f32_e32 v185, 0.5, v185
	v_mul_f32_e32 v182, v182, v138
	v_mul_f32_e32 v183, v183, v139
	v_mul_f32_e32 v184, v184, v140
	v_mul_f32_e32 v185, v185, v141
	v_add_f32_e32 v110, v225, v110
	v_add_f32_e32 v111, v226, v111
	v_add_f32_e32 v112, v227, v112
	v_add_f32_e32 v113, v228, v113
	v_mul_f32_e32 v110, v110, v182
	v_mul_f32_e32 v111, v111, v183
	v_mul_f32_e32 v112, v112, v184
	v_mul_f32_e32 v113, v113, v185
	v_cvt_pk_bf16_f32 v110, v110, v110
	v_cvt_pk_bf16_f32 v111, v111, v111
	v_cvt_pk_bf16_f32 v112, v112, v112
	v_cvt_pk_bf16_f32 v113, v113, v113
	v_mul_f32_e32 v138, v186, v186
	v_mul_f32_e32 v139, v187, v187
	v_mul_f32_e32 v140, v188, v188
	v_mul_f32_e32 v141, v189, v189
	v_mul_f32_e32 v138, v138, v186
	v_mul_f32_e32 v139, v139, v187
	v_mul_f32_e32 v140, v140, v188
	v_mul_f32_e32 v141, v141, v189
	v_fma_f32 v138, v202, v138, v186
	v_fma_f32 v139, v202, v139, v187
	v_fma_f32 v140, v202, v140, v188
	v_fma_f32 v141, v202, v141, v189
	v_mul_f32_e32 v138, 0x40135761, v138
	v_mul_f32_e32 v139, 0x40135761, v139
	v_mul_f32_e32 v140, 0x40135761, v140
	v_mul_f32_e32 v141, 0x40135761, v141
	v_exp_f32_e32 v138, v138
	v_exp_f32_e32 v139, v139
	v_exp_f32_e32 v140, v140
	v_exp_f32_e32 v141, v141
	s_nop 0
	v_add_f32_e32 v138, 1.0, v138
	v_add_f32_e32 v139, 1.0, v139
	v_add_f32_e32 v140, 1.0, v140
	v_add_f32_e32 v141, 1.0, v141
	v_rcp_f32_e32 v138, v138
	v_rcp_f32_e32 v139, v139
	v_rcp_f32_e32 v140, v140
	v_rcp_f32_e32 v141, v141
	s_nop 0
	v_fma_f32 v138, -2.0, v138, 1.0
	v_fma_f32 v139, -2.0, v139, 1.0
	v_fma_f32 v140, -2.0, v140, 1.0
	v_fma_f32 v141, -2.0, v141, 1.0
	v_add_f32_e32 v138, 1.0, v138
	v_add_f32_e32 v139, 1.0, v139
	v_add_f32_e32 v140, 1.0, v140
	v_add_f32_e32 v141, 1.0, v141
	v_mul_f32_e32 v186, 0.5, v186
	v_mul_f32_e32 v187, 0.5, v187
; __device__ __forceinline__ void lru_tile(const Params& P, int chunk, int head, int pass, char* smem_raw) {
;     ...
;             const float hfv = hfp[i];
;             const float g = gp[i];
;             const float tz = 0.7978845608028654f * (g + 0.044715f * g * g * g);
;             const float th = 1.f - 2.f * __builtin_amdgcn_rcpf(1.f + __expf(2.f * tz));
;             const float ge = 0.5f * g * (1.f + th);
;             P.cat[row * 1024 + gch] = f2bf((hfv + h) * ge);
;           }
;         }
	v_mul_f32_e32 v188, 0.5, v188
	v_mul_f32_e32 v189, 0.5, v189
	v_mul_f32_e32 v186, v186, v138
	v_mul_f32_e32 v187, v187, v139
	v_mul_f32_e32 v188, v188, v140
	v_mul_f32_e32 v189, v189, v141
	v_add_f32_e32 v114, v229, v114
	v_add_f32_e32 v115, v230, v115
	v_add_f32_e32 v116, v231, v116
	v_add_f32_e32 v117, v232, v117
	v_mul_f32_e32 v114, v114, v186
	v_mul_f32_e32 v115, v115, v187
	v_mul_f32_e32 v116, v116, v188
	v_mul_f32_e32 v117, v117, v189
	v_cvt_pk_bf16_f32 v114, v114, v114
	v_cvt_pk_bf16_f32 v115, v115, v115
	v_cvt_pk_bf16_f32 v116, v116, v116
	v_cvt_pk_bf16_f32 v117, v117, v117
	v_mul_f32_e32 v138, v190, v190
	v_mul_f32_e32 v139, v191, v191
	v_mul_f32_e32 v140, v192, v192
	v_mul_f32_e32 v141, v193, v193
	v_mul_f32_e32 v138, v138, v190
	v_mul_f32_e32 v139, v139, v191
	v_mul_f32_e32 v140, v140, v192
	v_mul_f32_e32 v141, v141, v193
	v_fma_f32 v138, v202, v138, v190
	v_fma_f32 v139, v202, v139, v191
	v_fma_f32 v140, v202, v140, v192
	v_fma_f32 v141, v202, v141, v193
	v_mul_f32_e32 v138, 0x40135761, v138
	v_mul_f32_e32 v139, 0x40135761, v139
	v_mul_f32_e32 v140, 0x40135761, v140
	v_mul_f32_e32 v141, 0x40135761, v141
	v_exp_f32_e32 v138, v138
	v_exp_f32_e32 v139, v139
	v_exp_f32_e32 v140, v140
	v_exp_f32_e32 v141, v141
	s_nop 0
	v_add_f32_e32 v138, 1.0, v138
	v_add_f32_e32 v139, 1.0, v139
	v_add_f32_e32 v140, 1.0, v140
	v_add_f32_e32 v141, 1.0, v141
	v_rcp_f32_e32 v138, v138
	v_rcp_f32_e32 v139, v139
	v_rcp_f32_e32 v140, v140
	v_rcp_f32_e32 v141, v141
	s_nop 0
	v_fma_f32 v138, -2.0, v138, 1.0
	v_fma_f32 v139, -2.0, v139, 1.0
	v_fma_f32 v140, -2.0, v140, 1.0
	v_fma_f32 v141, -2.0, v141, 1.0
	v_add_f32_e32 v138, 1.0, v138
	v_add_f32_e32 v139, 1.0, v139
	v_add_f32_e32 v140, 1.0, v140
	v_add_f32_e32 v141, 1.0, v141
	v_mul_f32_e32 v190, 0.5, v190
	v_mul_f32_e32 v191, 0.5, v191
	v_mul_f32_e32 v192, 0.5, v192
	v_mul_f32_e32 v193, 0.5, v193
	v_mul_f32_e32 v190, v190, v138
	v_mul_f32_e32 v191, v191, v139
	v_mul_f32_e32 v192, v192, v140
	v_mul_f32_e32 v193, v193, v141
	v_add_f32_e32 v118, v233, v118
	v_add_f32_e32 v119, v234, v119
	v_add_f32_e32 v120, v235, v120
	v_add_f32_e32 v121, v236, v121
	v_mul_f32_e32 v118, v118, v190
	v_mul_f32_e32 v119, v119, v191
	v_mul_f32_e32 v120, v120, v192
	v_mul_f32_e32 v121, v121, v193
	v_cvt_pk_bf16_f32 v118, v118, v118
	v_cvt_pk_bf16_f32 v119, v119, v119
	v_cvt_pk_bf16_f32 v120, v120, v120
	v_cvt_pk_bf16_f32 v121, v121, v121
	s_lshl_b32 s0, s71, 18
	s_lshl_b32 s1, s56, 1
	s_add_u32 s0, s0, s1
	s_add_u32 s4, s12, s0
	s_addc_u32 s5, s13, 0
	global_store_short v237, v90, s[4:5]
	s_add_u32 s4, s4, 0x800
	s_addc_u32 s5, s5, 0
	global_store_short v237, v91, s[4:5]
	s_add_u32 s4, s4, 0x800
	s_addc_u32 s5, s5, 0
	global_store_short v237, v92, s[4:5]
	s_add_u32 s4, s4, 0x800
	s_addc_u32 s5, s5, 0
	global_store_short v237, v93, s[4:5]
	s_add_u32 s4, s4, 0x800
	s_addc_u32 s5, s5, 0
	global_store_short v237, v94, s[4:5]
	s_add_u32 s4, s4, 0x800
	s_addc_u32 s5, s5, 0
	global_store_short v237, v95, s[4:5]
	s_add_u32 s4, s4, 0x800
	s_addc_u32 s5, s5, 0
	global_store_short v237, v96, s[4:5]
	s_add_u32 s4, s4, 0x800
	s_addc_u32 s5, s5, 0
	global_store_short v237, v97, s[4:5]
	s_add_u32 s4, s4, 0x800
	s_addc_u32 s5, s5, 0
	global_store_short v237, v98, s[4:5]
	s_add_u32 s4, s4, 0x800
	s_addc_u32 s5, s5, 0
	global_store_short v237, v99, s[4:5]
	s_add_u32 s4, s4, 0x800
	s_addc_u32 s5, s5, 0
	global_store_short v237, v100, s[4:5]
	s_add_u32 s4, s4, 0x800
	s_addc_u32 s5, s5, 0
	global_store_short v237, v101, s[4:5]
	s_add_u32 s4, s4, 0x800
	s_addc_u32 s5, s5, 0
	global_store_short v237, v102, s[4:5]
	s_add_u32 s4, s4, 0x800
	s_addc_u32 s5, s5, 0
	global_store_short v237, v103, s[4:5]
	s_add_u32 s4, s4, 0x800
	s_addc_u32 s5, s5, 0
	global_store_short v237, v104, s[4:5]
	s_add_u32 s4, s4, 0x800
	s_addc_u32 s5, s5, 0
	global_store_short v237, v105, s[4:5]
	s_add_u32 s4, s4, 0x800
	s_addc_u32 s5, s5, 0
	global_store_short v237, v106, s[4:5]
	s_add_u32 s4, s4, 0x800
	s_addc_u32 s5, s5, 0
	global_store_short v237, v107, s[4:5]
	s_add_u32 s4, s4, 0x800
	s_addc_u32 s5, s5, 0
	global_store_short v237, v108, s[4:5]
	s_add_u32 s4, s4, 0x800
	s_addc_u32 s5, s5, 0
	global_store_short v237, v109, s[4:5]
	s_add_u32 s4, s4, 0x800
	s_addc_u32 s5, s5, 0
	global_store_short v237, v110, s[4:5]
	s_add_u32 s4, s4, 0x800
	s_addc_u32 s5, s5, 0
	global_store_short v237, v111, s[4:5]
	s_add_u32 s4, s4, 0x800
	s_addc_u32 s5, s5, 0
	global_store_short v237, v112, s[4:5]
	s_add_u32 s4, s4, 0x800
	s_addc_u32 s5, s5, 0
	global_store_short v237, v113, s[4:5]
	s_add_u32 s4, s4, 0x800
	s_addc_u32 s5, s5, 0
	global_store_short v237, v114, s[4:5]
	s_add_u32 s4, s4, 0x800
	s_addc_u32 s5, s5, 0
	global_store_short v237, v115, s[4:5]
	s_add_u32 s4, s4, 0x800
	s_addc_u32 s5, s5, 0
	global_store_short v237, v116, s[4:5]
	s_add_u32 s4, s4, 0x800
	s_addc_u32 s5, s5, 0
	global_store_short v237, v117, s[4:5]
	s_add_u32 s4, s4, 0x800
	s_addc_u32 s5, s5, 0
	global_store_short v237, v118, s[4:5]
	s_add_u32 s4, s4, 0x800
	s_addc_u32 s5, s5, 0
	global_store_short v237, v119, s[4:5]
	s_add_u32 s4, s4, 0x800
	s_addc_u32 s5, s5, 0
	global_store_short v237, v120, s[4:5]
	s_add_u32 s4, s4, 0x800
	s_addc_u32 s5, s5, 0
	global_store_short v237, v121, s[4:5]
	s_add_u32 s69, s69, 1
	s_cmp_lt_u32 s69, s70
	s_cbranch_scc1 .Lmy_lrub_tile
	s_waitcnt lgkmcnt(0)
	s_barrier
	s_branch .LBB0_680
